# dead rstd-reduction VALU ops in in-proj epilogues turned into s_nop (partial dead-code pass)
# speedup vs baseline: 1.0050x; 1.0004x over previous
; __device__ __forceinline__ void row_rstd8(const float* ssp, int row0, int fq, float (&rs)[2][4]) {
; #pragma unroll
;     for (int ai = 0; ai < 2; ++ai) {
;         f32x4 a[4], b[4];
; #pragma unroll
;         for (int m = 0; m < 4; ++m) { const float* q = ssp + (size_t)(row0 + ai * HALF + m * 16) * 32 + fq * 8; a[m] = *(const f32x4*)q; b[m] = *(const f32x4*)(q + 4); }
; #pragma unroll
;         for (int m = 0; m < 4; ++m) {
;             float s = ((a[m][0] + a[m][1]) + (a[m][2] + a[m][3])) + ((b[m][0] + b[m][1]) + (b[m][2] + b[m][3]));
;             s += __shfl_xor(s, 16); s += __shfl_xor(s, 32);
;             rs[ai][m] = rsqrtf(s * (1.0f / D) + 1e-6f);
;         }
;     }
; }
;     template <int ACT> __device__ __forceinline__ void gated(const f32x4 (&acc)[2][2][4][2], bf16_t* base, int ld, int colbase, int row0, int cl) const {
;         const int fq = (cl >> 3) & 3;
;         const float* ssin = (const float*)(ws + OFF_SUMSQ) + (size_t)ssi * SS_SLOT;
;         float rsv[2][4];
;         row_rstd8(ssin, row0, fq, rsv);
.LBB0_577:
	s_and_b64 vcc, exec, s[44:45]
	s_cbranch_vccz .LBB0_579
	v_cmp_lt_i32_e32 vcc, v232, v231
	v_ashrrev_i32_e32 v163, 31, v162
	v_or_b32_e32 v202, 16, v162
	v_cndmask_b32_e32 v130, v229, v232, vcc
	v_cmp_lt_i32_e32 vcc, v230, v231
	v_lshlrev_b32_e32 v205, 2, v130
	v_ashrrev_i32_e32 v203, 31, v202
	v_cndmask_b32_e32 v130, v229, v230, vcc
	v_lshlrev_b32_e32 v177, 2, v130
	s_waitcnt lgkmcnt(0)
	v_lshlrev_b64 v[130:131], 7, v[162:163]
	v_lshl_add_u64 v[134:135], v[190:191], 0, v[130:131]
	s_nop 0
	s_nop 0
	s_nop 0
	v_lshlrev_b64 v[138:139], 7, v[202:203]
	v_lshl_add_u64 v[142:143], v[190:191], 0, v[138:139]
	s_nop 0
	s_nop 0
	s_nop 0
	v_or_b32_e32 v172, 32, v162
	v_ashrrev_i32_e32 v173, 31, v172
	v_lshlrev_b64 v[146:147], 7, v[172:173]
	v_or_b32_e32 v168, 48, v162
	v_lshl_add_u64 v[150:151], v[190:191], 0, v[146:147]
	v_ashrrev_i32_e32 v169, 31, v168
	s_nop 0
	s_nop 0
	s_nop 0
	v_lshlrev_b64 v[154:155], 7, v[168:169]
	v_lshl_add_u64 v[158:159], v[190:191], 0, v[154:155]
	s_nop 0
	s_nop 0
	s_nop 0
	s_mov_b32 s30, 0x358637bd
	v_mov_b64_e32 v[208:209], s[30:31]
	v_add_u32_e32 v174, 0x80, v162
	v_ashrrev_i32_e32 v175, 31, v174
	v_add_u32_e32 v170, 0x90, v162
	v_ashrrev_i32_e32 v171, 31, v170
	v_add_u32_e32 v166, 0xa0, v162
	v_ashrrev_i32_e32 v167, 31, v166
	s_lshl_b32 s58, s82, 7
	s_ashr_i32 s59, s58, 31
	s_nop 0
	v_mov_b32_e32 v164, v130
	v_mov_b32_e32 v165, v134
	v_mov_b32_e32 v134, v131
	v_pk_add_f32 v[130:131], v[164:165], v[134:135]
	v_mov_b32_e32 v134, v132
	v_mov_b32_e32 v135, v136
	v_mov_b32_e32 v136, v133
	v_pk_add_f32 v[132:133], v[134:135], v[136:137]
	v_mov_b32_e32 v134, v140
	v_pk_add_f32 v[130:131], v[130:131], v[132:133]
	v_mov_b32_e32 v132, v138
	v_mov_b32_e32 v133, v142
	v_mov_b32_e32 v142, v139
	v_mov_b32_e32 v135, v144
	v_mov_b32_e32 v144, v141
	v_pk_add_f32 v[132:133], v[132:133], v[142:143]
	v_pk_add_f32 v[134:135], v[134:135], v[144:145]
	v_add_u32_e32 v164, 0xb0, v162
	v_pk_add_f32 v[132:133], v[132:133], v[134:135]
	v_mov_b32_e32 v135, v130
	v_mov_b32_e32 v134, v132
	v_mov_b32_e32 v130, v133
	v_pk_add_f32 v[130:131], v[134:135], v[130:131]
	s_nop 0
	s_nop 0
	v_mov_b32_e32 v134, v156
	v_mov_b32_e32 v135, v160
	v_mov_b32_e32 v160, v157
	v_pk_add_f32 v[134:135], v[134:135], v[160:161]
	s_waitcnt lgkmcnt(0)
	v_pk_add_f32 v[130:131], v[130:131], v[132:133]
	s_nop 0
	s_nop 0
	v_ashrrev_i32_e32 v165, 31, v164
	s_waitcnt lgkmcnt(0)
	v_pk_add_f32 v[130:131], v[130:131], v[132:133]
	s_nop 0
	v_pk_fma_f32 v[130:131], v[130:131], s[22:23], v[208:209] op_sel_hi:[1,0,0]
	v_mov_b32_e32 v133, v152
	s_nop 0
	s_nop 0
	v_cmp_gt_f32_e32 vcc, s23, v130
	v_mov_b32_e32 v152, v149
	s_nop 0
	s_nop 0
	s_nop 0
	s_nop 0
	s_nop 0
	ds_read_b32 v206, v242 offset:0
	s_nop 0
	s_nop 0
	s_nop 0
	v_mov_b32_e32 v132, v148
	v_pk_add_f32 v[132:133], v[132:133], v[152:153]
	s_nop 0
	s_nop 0
	ds_read_b32 v204, v242 offset:64
	v_mov_b32_e32 v130, v146
	v_mov_b32_e32 v131, v150
	v_mov_b32_e32 v150, v147
	v_pk_add_f32 v[130:131], v[130:131], v[150:151]
	s_nop 0
	v_pk_add_f32 v[130:131], v[130:131], v[132:133]
	v_mov_b32_e32 v132, v154
	v_mov_b32_e32 v133, v158
	v_mov_b32_e32 v158, v155
	v_pk_add_f32 v[132:133], v[132:133], v[158:159]
	v_lshlrev_b64 v[154:155], 7, v[164:165]
	v_pk_add_f32 v[132:133], v[132:133], v[134:135]
	v_mov_b32_e32 v135, v130
	v_mov_b32_e32 v134, v132
	v_mov_b32_e32 v130, v133
	v_pk_add_f32 v[130:131], v[134:135], v[130:131]
	s_nop 0
	s_nop 0
	v_lshl_add_u64 v[154:155], v[190:191], 0, v[154:155]
	s_waitcnt lgkmcnt(0)
	v_pk_add_f32 v[130:131], v[130:131], v[132:133]
	s_nop 0
	s_nop 0
	s_waitcnt lgkmcnt(0)
	v_pk_add_f32 v[130:131], v[130:131], v[132:133]
	s_nop 0
	v_pk_fma_f32 v[130:131], v[130:131], s[22:23], v[208:209] op_sel_hi:[1,0,0]
	s_nop 0
	v_mul_f32_e32 v132, 0x4b800000, v131
	v_cmp_gt_f32_e64 s[44:45], s23, v131
	v_cmp_gt_f32_e32 vcc, s23, v130
	s_nop 0
	v_cndmask_b32_e64 v131, v131, v132, s[44:45]
	v_rsq_f32_e32 v131, v131
	s_nop 0
	v_mul_f32_e32 v132, 0x45800000, v131
	s_nop 0
	ds_read_b32 v178, v242 offset:128
	v_mul_f32_e32 v131, 0x4b800000, v130
	v_cndmask_b32_e32 v130, v130, v131, vcc
	v_rsq_f32_e32 v130, v130
	s_nop 0
	v_mul_f32_e32 v131, 0x45800000, v130
	s_nop 0
	ds_read_b32 v176, v242 offset:192
	v_lshlrev_b64 v[130:131], 7, v[174:175]
	v_lshl_add_u64 v[130:131], v[190:191], 0, v[130:131]
	s_nop 0
	s_nop 0
	v_lshlrev_b64 v[130:131], 7, v[170:171]
	v_lshl_add_u64 v[130:131], v[190:191], 0, v[130:131]
	s_nop 0
	s_nop 0
	v_lshlrev_b64 v[130:131], 7, v[166:167]
	v_lshl_add_u64 v[130:131], v[190:191], 0, v[130:131]
	s_nop 0
	s_nop 0
	s_nop 0
	s_nop 0
	s_nop 0
	s_nop 0
	s_nop 0
	s_nop 0
	v_mov_b32_e32 v210, v142
	s_nop 0
	v_mov_b32_e32 v211, v138
	v_mov_b32_e32 v138, v143
	v_mov_b32_e32 v142, v144
	v_mov_b32_e32 v143, v140
	v_mov_b32_e32 v140, v145
	v_pk_add_f32 v[138:139], v[210:211], v[138:139]
	v_pk_add_f32 v[140:141], v[142:143], v[140:141]
	s_nop 0
	v_mov_b32_e32 v142, v152
	v_pk_add_f32 v[138:139], v[138:139], v[140:141]
	v_mov_b32_e32 v140, v150
	s_nop 0
	v_mov_b32_e32 v141, v146
	v_mov_b32_e32 v146, v151
	v_mov_b32_e32 v143, v148
	v_mov_b32_e32 v148, v153
	v_pk_add_f32 v[140:141], v[140:141], v[146:147]
	v_pk_add_f32 v[142:143], v[142:143], v[148:149]
	s_waitcnt lgkmcnt(0)
; __device__ __forceinline__ float silu_f(float x) { return x * __builtin_amdgcn_rcpf(1.0f + __expf(-x)); }
; __device__ __forceinline__ void row_rstd8(const float* ssp, int row0, int fq, float (&rs)[2][4]) {
;     ...
;         for (int m = 0; m < 4; ++m) {
;             float s = ((a[m][0] + a[m][1]) + (a[m][2] + a[m][3])) + ((b[m][0] + b[m][1]) + (b[m][2] + b[m][3]));
;             s += __shfl_xor(s, 16); s += __shfl_xor(s, 32);
;             rs[ai][m] = rsqrtf(s * (1.0f / D) + 1e-6f);
;         }
;     template <int ACT> __device__ __forceinline__ void gated(const f32x4 (&acc)[2][2][4][2], bf16_t* base, int ld, int colbase, int row0, int cl) const {
;     ...
; #pragma unroll
;         for (int ai = 0; ai < 2; ++ai)
; #pragma unroll
;             for (int m = 0; m < 4; ++m) {
;                 const int row = row0 + ai * HALF + m * 16;
;                 const float rs = rsv[ai][m];
;                 float o[8];
; #pragma unroll
;                 for (int n = 0; n < 2; ++n)
; #pragma unroll
;                     for (int j = 0; j < 4; ++j) {
;                         const float g = acc[ai][0][m][n][j] * rs, u = acc[ai][1][m][n][j] * rs;
;                         o[n * 4 + j] = (ACT ? silu_f(g) : g) * u;
;                     }
;                 *(u32x4*)(base + (size_t)row * ld + colbase + cl) = pack8(o);
	v_pk_mul_f32 v[144:145], v[114:115], v[206:207] op_sel_hi:[1,0]
	v_pk_add_f32 v[140:141], v[140:141], v[142:143]
	v_mov_b32_e32 v143, v138
	v_mov_b32_e32 v142, v140
	v_mov_b32_e32 v138, v141
	v_pk_add_f32 v[138:139], v[142:143], v[138:139]
	s_nop 0
	v_mov_b32_e32 v142, v134
	s_nop 0
	v_mov_b32_e32 v143, v130
	v_mov_b32_e32 v130, v135
	v_mov_b32_e32 v134, v136
	v_mov_b32_e32 v135, v132
	v_mov_b32_e32 v132, v137
	v_pk_add_f32 v[130:131], v[142:143], v[130:131]
	v_pk_add_f32 v[132:133], v[134:135], v[132:133]
	s_nop 0
	v_mov_b32_e32 v134, v160
	v_pk_add_f32 v[130:131], v[130:131], v[132:133]
	v_mov_b32_e32 v132, v158
	s_nop 0
	v_mov_b32_e32 v133, v154
	v_mov_b32_e32 v154, v159
	v_mov_b32_e32 v135, v156
	v_mov_b32_e32 v156, v161
	v_pk_add_f32 v[132:133], v[132:133], v[154:155]
	v_pk_add_f32 v[134:135], v[134:135], v[156:157]
	v_pk_mul_f32 v[136:137], v[126:127], v[206:207] op_sel_hi:[1,0]
	v_pk_add_f32 v[132:133], v[132:133], v[134:135]
	v_mov_b32_e32 v135, v130
	v_mov_b32_e32 v134, v132
	v_mov_b32_e32 v130, v133
	v_pk_add_f32 v[130:131], v[134:135], v[130:131]
	s_nop 0
	s_nop 0
	v_pk_mul_f32 v[146:147], v[116:117], v[206:207] op_sel_hi:[1,0]
	s_nop 0
	s_nop 0
	v_pk_mul_f32 v[148:149], v[106:107], v[206:207] op_sel_hi:[1,0]
	s_waitcnt lgkmcnt(2)
	v_pk_add_f32 v[130:131], v[130:131], v[132:133]
	s_nop 0
	s_nop 0
	s_waitcnt lgkmcnt(2)
	v_pk_add_f32 v[138:139], v[138:139], v[140:141]
	s_nop 0
	s_nop 0
	v_pk_mul_f32 v[150:151], v[108:109], v[206:207] op_sel_hi:[1,0]
	s_waitcnt lgkmcnt(2)
	v_pk_add_f32 v[130:131], v[130:131], v[132:133]
	v_mul_f32_e32 v133, 0xbfb8aa3b, v136
	v_exp_f32_e32 v133, v133
	s_waitcnt lgkmcnt(0)
	v_pk_add_f32 v[138:139], v[138:139], v[140:141]
	v_pk_fma_f32 v[130:131], v[130:131], s[22:23], v[208:209] op_sel_hi:[1,0,0]
	v_pk_fma_f32 v[138:139], v[138:139], s[22:23], v[208:209] op_sel_hi:[1,0,0]
	v_add_f32_e32 v133, 1.0, v133
	v_rcp_f32_e32 v142, v133
	v_mul_f32_e32 v133, 0xbfb8aa3b, v137
	v_exp_f32_e32 v133, v133
	s_nop 0
	s_nop 0
	v_cmp_gt_f32_e32 vcc, s23, v138
	v_add_f32_e32 v133, 1.0, v133
	v_rcp_f32_e32 v143, v133
	s_nop 0
	s_nop 0
	s_nop 0
	v_pk_mul_f32 v[136:137], v[136:137], v[142:143]
	v_pk_mul_f32 v[142:143], v[128:129], v[206:207] op_sel_hi:[1,0]
	v_pk_mul_f32 v[136:137], v[144:145], v[136:137]
	v_mul_f32_e32 v133, 0xbfb8aa3b, v142
	v_exp_f32_e32 v133, v133
	s_nop 0
	s_nop 0
	ds_read_b32 v140, v242 offset:512
	v_mul_f32_e32 v139, 0x4b800000, v138
	v_add_f32_e32 v133, 1.0, v133
	v_rcp_f32_e32 v144, v133
	v_mul_f32_e32 v133, 0xbfb8aa3b, v143
	v_exp_f32_e32 v133, v133
	v_cmp_gt_f32_e64 s[44:45], s23, v131
	v_cndmask_b32_e32 v138, v138, v139, vcc
	v_rsq_f32_e32 v138, v138
	v_add_f32_e32 v133, 1.0, v133
	v_rcp_f32_e32 v145, v133
	s_nop 0
	s_nop 0
	v_mul_f32_e32 v139, 0x45800000, v138
	v_pk_mul_f32 v[142:143], v[142:143], v[144:145]
	s_nop 0
	ds_read_b32 v138, v242 offset:576
	v_pk_mul_f32 v[144:145], v[146:147], v[142:143]
	v_pk_mul_f32 v[142:143], v[122:123], v[206:207] op_sel_hi:[1,0]
	s_nop 0
	v_mul_f32_e32 v133, 0xbfb8aa3b, v142
	v_exp_f32_e32 v133, v133
	v_cmp_gt_f32_e32 vcc, s23, v130
	s_nop 0
	ds_read_b32 v134, v242 offset:640
	v_mul_f32_e32 v131, 0x4b800000, v130
	v_add_f32_e32 v133, 1.0, v133
	v_rcp_f32_e32 v146, v133
	v_mul_f32_e32 v133, 0xbfb8aa3b, v143
	v_exp_f32_e32 v133, v133
	v_cndmask_b32_e32 v130, v130, v131, vcc
	v_rsq_f32_e32 v130, v130
	v_add_f32_e32 v133, 1.0, v133
	v_rcp_f32_e32 v147, v133
	v_mul_f32_e32 v131, 0x45800000, v130
	s_nop 0
	ds_read_b32 v132, v242 offset:704
	v_lshl_add_u64 v[130:131], s[58:59], 1, v[188:189]
	v_pk_mul_f32 v[142:143], v[142:143], v[146:147]
	s_movk_i32 s58, 0x2c00
	v_pk_mul_f32 v[146:147], v[148:149], v[142:143]
	v_pk_mul_f32 v[142:143], v[124:125], v[206:207] op_sel_hi:[1,0]
	s_nop 0
	v_mul_f32_e32 v133, 0xbfb8aa3b, v142
	v_exp_f32_e32 v133, v133
	s_nop 0
	v_add_f32_e32 v133, 1.0, v133
	v_rcp_f32_e32 v148, v133
	v_mul_f32_e32 v133, 0xbfb8aa3b, v143
	v_exp_f32_e32 v133, v133
	s_nop 0
	v_add_f32_e32 v133, 1.0, v133
	v_rcp_f32_e32 v149, v133
	s_nop 0
	v_pk_mul_f32 v[142:143], v[142:143], v[148:149]
	s_nop 0
	v_pk_mul_f32 v[148:149], v[150:151], v[142:143]
	v_cvt_pk_bf16_f32 v142, v136, v137
	v_cvt_pk_bf16_f32 v143, v144, v145
	v_cvt_pk_bf16_f32 v144, v146, v147
	v_cvt_pk_bf16_f32 v145, v148, v149
	v_mad_i64_i32 v[136:137], s[44:45], v162, s58, v[130:131]
	global_store_dwordx4 v[136:137], v[142:145], off
	s_waitcnt lgkmcnt(0)
	v_pk_mul_f32 v[136:137], v[118:119], v[204:205] op_sel_hi:[1,0]
	v_pk_mul_f32 v[146:147], v[100:101], v[204:205] op_sel_hi:[1,0]
	v_mul_f32_e32 v133, 0xbfb8aa3b, v136
	v_exp_f32_e32 v133, v133
	v_pk_mul_f32 v[144:145], v[98:99], v[204:205] op_sel_hi:[1,0]
	v_pk_mul_f32 v[148:149], v[90:91], v[204:205] op_sel_hi:[1,0]
	v_pk_mul_f32 v[150:151], v[92:93], v[204:205] op_sel_hi:[1,0]
	v_add_f32_e32 v133, 1.0, v133
	v_rcp_f32_e32 v142, v133
	v_mul_f32_e32 v133, 0xbfb8aa3b, v137
	v_exp_f32_e32 v133, v133
	s_nop 0
	v_add_f32_e32 v133, 1.0, v133
	v_rcp_f32_e32 v143, v133
	s_nop 0
	v_pk_mul_f32 v[136:137], v[136:137], v[142:143]
	v_pk_mul_f32 v[142:143], v[120:121], v[204:205] op_sel_hi:[1,0]
	v_pk_mul_f32 v[136:137], v[144:145], v[136:137]
	v_mul_f32_e32 v133, 0xbfb8aa3b, v142
	v_exp_f32_e32 v133, v133
	s_nop 0
	v_add_f32_e32 v133, 1.0, v133
	v_rcp_f32_e32 v144, v133
	v_mul_f32_e32 v133, 0xbfb8aa3b, v143
	v_exp_f32_e32 v133, v133
	s_nop 0
	v_add_f32_e32 v133, 1.0, v133
	v_rcp_f32_e32 v145, v133
	s_nop 0
	v_pk_mul_f32 v[142:143], v[142:143], v[144:145]
	s_nop 0
	v_pk_mul_f32 v[144:145], v[146:147], v[142:143]
	v_pk_mul_f32 v[142:143], v[110:111], v[204:205] op_sel_hi:[1,0]
	s_nop 0
	v_mul_f32_e32 v133, 0xbfb8aa3b, v142
	v_exp_f32_e32 v133, v133
	s_nop 0
	v_add_f32_e32 v133, 1.0, v133
	v_rcp_f32_e32 v146, v133
	v_mul_f32_e32 v133, 0xbfb8aa3b, v143
	v_exp_f32_e32 v133, v133
	s_nop 0
	v_add_f32_e32 v133, 1.0, v133
	v_rcp_f32_e32 v147, v133
	s_nop 0
	v_pk_mul_f32 v[142:143], v[142:143], v[146:147]
	s_nop 0
	v_pk_mul_f32 v[146:147], v[148:149], v[142:143]
	v_pk_mul_f32 v[142:143], v[112:113], v[204:205] op_sel_hi:[1,0]
	s_nop 0
	v_mul_f32_e32 v133, 0xbfb8aa3b, v142
	v_exp_f32_e32 v133, v133
	s_nop 0
	v_add_f32_e32 v133, 1.0, v133
	v_rcp_f32_e32 v148, v133
	v_mul_f32_e32 v133, 0xbfb8aa3b, v143
	v_exp_f32_e32 v133, v133
	s_nop 0
	v_add_f32_e32 v133, 1.0, v133
	v_rcp_f32_e32 v149, v133
	s_nop 0
	v_pk_mul_f32 v[142:143], v[142:143], v[148:149]
	s_nop 0
	v_pk_mul_f32 v[148:149], v[150:151], v[142:143]
	v_cvt_pk_bf16_f32 v142, v136, v137
	v_cvt_pk_bf16_f32 v143, v144, v145
	v_cvt_pk_bf16_f32 v144, v146, v147
	v_cvt_pk_bf16_f32 v145, v148, v149
	v_mad_i64_i32 v[136:137], s[44:45], v202, s58, v[130:131]
	global_store_dwordx4 v[136:137], v[142:145], off
	s_waitcnt lgkmcnt(0)
; __device__ __forceinline__ float silu_f(float x) { return x * __builtin_amdgcn_rcpf(1.0f + __expf(-x)); }
;     template <int ACT> __device__ __forceinline__ void gated(const f32x4 (&acc)[2][2][4][2], bf16_t* base, int ld, int colbase, int row0, int cl) const {
;     ...
; #pragma unroll
;         for (int ai = 0; ai < 2; ++ai)
; #pragma unroll
;             for (int m = 0; m < 4; ++m) {
;                 const int row = row0 + ai * HALF + m * 16;
;                 const float rs = rsv[ai][m];
;                 float o[8];
; #pragma unroll
;                 for (int n = 0; n < 2; ++n)
; #pragma unroll
;                     for (int j = 0; j < 4; ++j) {
;                         const float g = acc[ai][0][m][n][j] * rs, u = acc[ai][1][m][n][j] * rs;
;                         o[n * 4 + j] = (ACT ? silu_f(g) : g) * u;
;                     }
;                 *(u32x4*)(base + (size_t)row * ld + colbase + cl) = pack8(o);
	v_pk_mul_f32 v[136:137], v[102:103], v[178:179] op_sel_hi:[1,0]
	v_pk_mul_f32 v[146:147], v[84:85], v[178:179] op_sel_hi:[1,0]
	v_mul_f32_e32 v133, 0xbfb8aa3b, v136
	v_exp_f32_e32 v133, v133
	v_pk_mul_f32 v[144:145], v[82:83], v[178:179] op_sel_hi:[1,0]
	v_pk_mul_f32 v[148:149], v[74:75], v[178:179] op_sel_hi:[1,0]
	v_pk_mul_f32 v[150:151], v[76:77], v[178:179] op_sel_hi:[1,0]
	v_add_f32_e32 v133, 1.0, v133
	v_rcp_f32_e32 v142, v133
	v_mul_f32_e32 v133, 0xbfb8aa3b, v137
	v_exp_f32_e32 v133, v133
	s_nop 0
	v_add_f32_e32 v133, 1.0, v133
	v_rcp_f32_e32 v143, v133
	s_nop 0
	v_pk_mul_f32 v[136:137], v[136:137], v[142:143]
	v_pk_mul_f32 v[142:143], v[104:105], v[178:179] op_sel_hi:[1,0]
	v_pk_mul_f32 v[136:137], v[144:145], v[136:137]
	v_mul_f32_e32 v133, 0xbfb8aa3b, v142
	v_exp_f32_e32 v133, v133
	s_nop 0
	v_add_f32_e32 v133, 1.0, v133
	v_rcp_f32_e32 v144, v133
	v_mul_f32_e32 v133, 0xbfb8aa3b, v143
	v_exp_f32_e32 v133, v133
	s_nop 0
	v_add_f32_e32 v133, 1.0, v133
	v_rcp_f32_e32 v145, v133
	s_nop 0
	v_pk_mul_f32 v[142:143], v[142:143], v[144:145]
	s_nop 0
	v_pk_mul_f32 v[144:145], v[146:147], v[142:143]
	v_pk_mul_f32 v[142:143], v[94:95], v[178:179] op_sel_hi:[1,0]
	s_nop 0
	v_mul_f32_e32 v133, 0xbfb8aa3b, v142
	v_exp_f32_e32 v133, v133
	s_nop 0
	v_add_f32_e32 v133, 1.0, v133
	v_rcp_f32_e32 v146, v133
	v_mul_f32_e32 v133, 0xbfb8aa3b, v143
	v_exp_f32_e32 v133, v133
	s_nop 0
	v_add_f32_e32 v133, 1.0, v133
	v_rcp_f32_e32 v147, v133
	s_nop 0
	v_pk_mul_f32 v[142:143], v[142:143], v[146:147]
	s_nop 0
	v_pk_mul_f32 v[146:147], v[148:149], v[142:143]
	v_pk_mul_f32 v[142:143], v[96:97], v[178:179] op_sel_hi:[1,0]
	s_nop 0
	v_mul_f32_e32 v133, 0xbfb8aa3b, v142
	v_exp_f32_e32 v133, v133
	s_nop 0
	v_add_f32_e32 v133, 1.0, v133
	v_rcp_f32_e32 v148, v133
	v_mul_f32_e32 v133, 0xbfb8aa3b, v143
	v_exp_f32_e32 v133, v133
	s_nop 0
	v_add_f32_e32 v133, 1.0, v133
	v_rcp_f32_e32 v149, v133
	s_nop 0
	v_pk_mul_f32 v[142:143], v[142:143], v[148:149]
	s_nop 0
	v_pk_mul_f32 v[148:149], v[150:151], v[142:143]
	v_cvt_pk_bf16_f32 v142, v136, v137
	v_cvt_pk_bf16_f32 v143, v144, v145
	v_cvt_pk_bf16_f32 v144, v146, v147
	v_cvt_pk_bf16_f32 v145, v148, v149
	v_mad_i64_i32 v[136:137], s[44:45], v172, s58, v[130:131]
	global_store_dwordx4 v[136:137], v[142:145], off
	s_waitcnt lgkmcnt(0)
	v_pk_mul_f32 v[136:137], v[86:87], v[176:177] op_sel_hi:[1,0]
	v_pk_mul_f32 v[146:147], v[72:73], v[176:177] op_sel_hi:[1,0]
	v_mul_f32_e32 v133, 0xbfb8aa3b, v136
	v_exp_f32_e32 v133, v133
	v_pk_mul_f32 v[144:145], v[70:71], v[176:177] op_sel_hi:[1,0]
	v_pk_mul_f32 v[148:149], v[66:67], v[176:177] op_sel_hi:[1,0]
	v_pk_mul_f32 v[150:151], v[68:69], v[176:177] op_sel_hi:[1,0]
	v_add_f32_e32 v133, 1.0, v133
	v_rcp_f32_e32 v142, v133
	v_mul_f32_e32 v133, 0xbfb8aa3b, v137
	v_exp_f32_e32 v133, v133
	s_nop 0
	v_add_f32_e32 v133, 1.0, v133
	v_rcp_f32_e32 v143, v133
	s_nop 0
	v_pk_mul_f32 v[136:137], v[136:137], v[142:143]
	v_pk_mul_f32 v[142:143], v[88:89], v[176:177] op_sel_hi:[1,0]
	v_pk_mul_f32 v[136:137], v[144:145], v[136:137]
	v_mul_f32_e32 v133, 0xbfb8aa3b, v142
	v_exp_f32_e32 v133, v133
	s_nop 0
	v_add_f32_e32 v133, 1.0, v133
	v_rcp_f32_e32 v144, v133
	v_mul_f32_e32 v133, 0xbfb8aa3b, v143
	v_exp_f32_e32 v133, v133
	s_nop 0
	v_add_f32_e32 v133, 1.0, v133
	v_rcp_f32_e32 v145, v133
	s_nop 0
	v_pk_mul_f32 v[142:143], v[142:143], v[144:145]
	s_nop 0
	v_pk_mul_f32 v[144:145], v[146:147], v[142:143]
	v_pk_mul_f32 v[142:143], v[78:79], v[176:177] op_sel_hi:[1,0]
	s_nop 0
	v_mul_f32_e32 v133, 0xbfb8aa3b, v142
	v_exp_f32_e32 v133, v133
	s_nop 0
	v_add_f32_e32 v133, 1.0, v133
	v_rcp_f32_e32 v146, v133
	v_mul_f32_e32 v133, 0xbfb8aa3b, v143
	v_exp_f32_e32 v133, v133
	s_nop 0
	v_add_f32_e32 v133, 1.0, v133
	v_rcp_f32_e32 v147, v133
	s_nop 0
	v_pk_mul_f32 v[142:143], v[142:143], v[146:147]
	s_nop 0
	v_pk_mul_f32 v[146:147], v[148:149], v[142:143]
	v_pk_mul_f32 v[142:143], v[80:81], v[176:177] op_sel_hi:[1,0]
	s_nop 0
	v_mul_f32_e32 v133, 0xbfb8aa3b, v142
	v_exp_f32_e32 v133, v133
	s_nop 0
	v_add_f32_e32 v133, 1.0, v133
	v_rcp_f32_e32 v148, v133
	v_mul_f32_e32 v133, 0xbfb8aa3b, v143
	v_exp_f32_e32 v133, v133
	s_nop 0
	v_add_f32_e32 v133, 1.0, v133
	v_rcp_f32_e32 v149, v133
	s_nop 0
	v_pk_mul_f32 v[142:143], v[142:143], v[148:149]
	s_nop 0
	v_pk_mul_f32 v[148:149], v[150:151], v[142:143]
	v_cvt_pk_bf16_f32 v142, v136, v137
	v_cvt_pk_bf16_f32 v143, v144, v145
	v_cvt_pk_bf16_f32 v144, v146, v147
	v_cvt_pk_bf16_f32 v145, v148, v149
	v_mad_i64_i32 v[136:137], s[44:45], v168, s58, v[130:131]
	global_store_dwordx4 v[136:137], v[142:145], off
	s_waitcnt lgkmcnt(0)
; __device__ __forceinline__ float silu_f(float x) { return x * __builtin_amdgcn_rcpf(1.0f + __expf(-x)); }
;     template <int ACT> __device__ __forceinline__ void gated(const f32x4 (&acc)[2][2][4][2], bf16_t* base, int ld, int colbase, int row0, int cl) const {
;     ...
; #pragma unroll
;         for (int ai = 0; ai < 2; ++ai)
; #pragma unroll
;             for (int m = 0; m < 4; ++m) {
;                 const int row = row0 + ai * HALF + m * 16;
;                 const float rs = rsv[ai][m];
;                 float o[8];
; #pragma unroll
;                 for (int n = 0; n < 2; ++n)
; #pragma unroll
;                     for (int j = 0; j < 4; ++j) {
;                         const float g = acc[ai][0][m][n][j] * rs, u = acc[ai][1][m][n][j] * rs;
;                         o[n * 4 + j] = (ACT ? silu_f(g) : g) * u;
;                     }
;                 *(u32x4*)(base + (size_t)row * ld + colbase + cl) = pack8(o);
	v_pk_mul_f32 v[136:137], v[62:63], v[140:141] op_sel_hi:[1,0]
	v_pk_mul_f32 v[146:147], v[48:49], v[140:141] op_sel_hi:[1,0]
	v_mul_f32_e32 v133, 0xbfb8aa3b, v136
	v_exp_f32_e32 v133, v133
	v_pk_mul_f32 v[144:145], v[46:47], v[140:141] op_sel_hi:[1,0]
	v_pk_mul_f32 v[148:149], v[42:43], v[140:141] op_sel_hi:[1,0]
	v_add_f32_e32 v133, 1.0, v133
	v_rcp_f32_e32 v142, v133
	v_mul_f32_e32 v133, 0xbfb8aa3b, v137
	v_exp_f32_e32 v133, v133
	s_nop 0
	v_add_f32_e32 v133, 1.0, v133
	v_rcp_f32_e32 v143, v133
	s_nop 0
	v_pk_mul_f32 v[136:137], v[136:137], v[142:143]
	v_pk_mul_f32 v[142:143], v[64:65], v[140:141] op_sel_hi:[1,0]
	v_pk_mul_f32 v[136:137], v[144:145], v[136:137]
	v_mul_f32_e32 v133, 0xbfb8aa3b, v142
	v_exp_f32_e32 v133, v133
	s_nop 0
	v_add_f32_e32 v133, 1.0, v133
	v_rcp_f32_e32 v144, v133
	v_mul_f32_e32 v133, 0xbfb8aa3b, v143
	v_exp_f32_e32 v133, v133
	s_nop 0
	v_add_f32_e32 v133, 1.0, v133
	v_rcp_f32_e32 v145, v133
	s_nop 0
	v_pk_mul_f32 v[142:143], v[142:143], v[144:145]
	v_pk_mul_f32 v[144:145], v[58:59], v[140:141] op_sel_hi:[1,0]
	v_pk_mul_f32 v[142:143], v[146:147], v[142:143]
	v_mul_f32_e32 v133, 0xbfb8aa3b, v144
	v_exp_f32_e32 v133, v133
	s_nop 0
	v_add_f32_e32 v133, 1.0, v133
	v_rcp_f32_e32 v146, v133
	v_mul_f32_e32 v133, 0xbfb8aa3b, v145
	v_exp_f32_e32 v133, v133
	s_nop 0
	v_add_f32_e32 v133, 1.0, v133
	v_rcp_f32_e32 v147, v133
	s_nop 0
	v_pk_mul_f32 v[144:145], v[144:145], v[146:147]
	v_pk_mul_f32 v[146:147], v[60:61], v[140:141] op_sel_hi:[1,0]
	v_pk_mul_f32 v[144:145], v[148:149], v[144:145]
	v_mul_f32_e32 v133, 0xbfb8aa3b, v146
	v_exp_f32_e32 v133, v133
	v_pk_mul_f32 v[140:141], v[44:45], v[140:141] op_sel_hi:[1,0]
	v_add_f32_e32 v133, 1.0, v133
	v_rcp_f32_e32 v148, v133
	v_mul_f32_e32 v133, 0xbfb8aa3b, v147
	v_exp_f32_e32 v133, v133
	s_nop 0
	v_add_f32_e32 v133, 1.0, v133
	v_rcp_f32_e32 v149, v133
	s_nop 0
	v_pk_mul_f32 v[146:147], v[146:147], v[148:149]
	s_nop 0
	v_pk_mul_f32 v[146:147], v[140:141], v[146:147]
	v_cvt_pk_bf16_f32 v140, v136, v137
	v_cvt_pk_bf16_f32 v141, v142, v143
	v_cvt_pk_bf16_f32 v142, v144, v145
	v_cvt_pk_bf16_f32 v143, v146, v147
	v_mad_i64_i32 v[136:137], s[44:45], v174, s58, v[130:131]
	global_store_dwordx4 v[136:137], v[140:143], off
	s_waitcnt lgkmcnt(0)
	v_pk_mul_f32 v[136:137], v[54:55], v[138:139] op_sel_hi:[1,0]
	v_pk_mul_f32 v[144:145], v[32:33], v[138:139] op_sel_hi:[1,0]
	v_mul_f32_e32 v133, 0xbfb8aa3b, v136
	v_exp_f32_e32 v133, v133
	v_pk_mul_f32 v[142:143], v[30:31], v[138:139] op_sel_hi:[1,0]
	v_pk_mul_f32 v[146:147], v[26:27], v[138:139] op_sel_hi:[1,0]
	v_add_f32_e32 v133, 1.0, v133
	v_rcp_f32_e32 v140, v133
	v_mul_f32_e32 v133, 0xbfb8aa3b, v137
	v_exp_f32_e32 v133, v133
	s_nop 0
	v_add_f32_e32 v133, 1.0, v133
	v_rcp_f32_e32 v141, v133
	s_nop 0
	v_pk_mul_f32 v[136:137], v[136:137], v[140:141]
	v_pk_mul_f32 v[140:141], v[56:57], v[138:139] op_sel_hi:[1,0]
	v_pk_mul_f32 v[136:137], v[142:143], v[136:137]
	v_mul_f32_e32 v133, 0xbfb8aa3b, v140
	v_exp_f32_e32 v133, v133
	v_cvt_pk_bf16_f32 v136, v136, v137
	v_add_f32_e32 v133, 1.0, v133
	v_rcp_f32_e32 v142, v133
	v_mul_f32_e32 v133, 0xbfb8aa3b, v141
	v_exp_f32_e32 v133, v133
	s_nop 0
	v_add_f32_e32 v133, 1.0, v133
	v_rcp_f32_e32 v143, v133
	s_nop 0
	v_pk_mul_f32 v[140:141], v[140:141], v[142:143]
	v_pk_mul_f32 v[142:143], v[50:51], v[138:139] op_sel_hi:[1,0]
	v_pk_mul_f32 v[140:141], v[144:145], v[140:141]
	v_mul_f32_e32 v133, 0xbfb8aa3b, v142
	v_exp_f32_e32 v133, v133
	v_cvt_pk_bf16_f32 v137, v140, v141
	v_mad_i64_i32 v[140:141], s[44:45], v170, s58, v[130:131]
	v_add_f32_e32 v133, 1.0, v133
	v_rcp_f32_e32 v144, v133
	v_mul_f32_e32 v133, 0xbfb8aa3b, v143
	v_exp_f32_e32 v133, v133
	s_nop 0
	v_add_f32_e32 v133, 1.0, v133
	v_rcp_f32_e32 v145, v133
	s_nop 0
	v_pk_mul_f32 v[142:143], v[142:143], v[144:145]
	v_pk_mul_f32 v[144:145], v[52:53], v[138:139] op_sel_hi:[1,0]
	v_pk_mul_f32 v[142:143], v[146:147], v[142:143]
	v_mul_f32_e32 v133, 0xbfb8aa3b, v144
	v_exp_f32_e32 v133, v133
	v_pk_mul_f32 v[138:139], v[28:29], v[138:139] op_sel_hi:[1,0]
	v_add_f32_e32 v133, 1.0, v133
	v_rcp_f32_e32 v146, v133
	v_mul_f32_e32 v133, 0xbfb8aa3b, v145
	v_exp_f32_e32 v133, v133
	s_nop 0
	v_add_f32_e32 v133, 1.0, v133
	v_rcp_f32_e32 v147, v133
	s_nop 0
	v_pk_mul_f32 v[144:145], v[144:145], v[146:147]
	s_nop 0
	v_pk_mul_f32 v[144:145], v[138:139], v[144:145]
	v_cvt_pk_bf16_f32 v138, v142, v143
	v_cvt_pk_bf16_f32 v139, v144, v145
	global_store_dwordx4 v[140:141], v[136:139], off
	s_waitcnt lgkmcnt(0)
; __device__ __forceinline__ float silu_f(float x) { return x * __builtin_amdgcn_rcpf(1.0f + __expf(-x)); }
;     template <int ACT> __device__ __forceinline__ void gated(const f32x4 (&acc)[2][2][4][2], bf16_t* base, int ld, int colbase, int row0, int cl) const {
;     ...
; #pragma unroll
;         for (int ai = 0; ai < 2; ++ai)
; #pragma unroll
;             for (int m = 0; m < 4; ++m) {
;                 const int row = row0 + ai * HALF + m * 16;
;                 const float rs = rsv[ai][m];
;                 float o[8];
; #pragma unroll
;                 for (int n = 0; n < 2; ++n)
; #pragma unroll
;                     for (int j = 0; j < 4; ++j) {
;                         const float g = acc[ai][0][m][n][j] * rs, u = acc[ai][1][m][n][j] * rs;
;                         o[n * 4 + j] = (ACT ? silu_f(g) : g) * u;
;                     }
;                 *(u32x4*)(base + (size_t)row * ld + colbase + cl) = pack8(o);
;             }
	v_pk_mul_f32 v[140:141], v[14:15], v[134:135] op_sel_hi:[1,0]
	v_pk_mul_f32 v[142:143], v[16:17], v[134:135] op_sel_hi:[1,0]
	v_pk_mul_f32 v[136:137], v[38:39], v[134:135] op_sel_hi:[1,0]
	v_pk_mul_f32 v[144:145], v[10:11], v[134:135] op_sel_hi:[1,0]
	v_mul_f32_e32 v133, 0xbfb8aa3b, v136
	v_exp_f32_e32 v133, v133
	s_nop 0
	v_add_f32_e32 v133, 1.0, v133
	v_rcp_f32_e32 v138, v133
	v_mul_f32_e32 v133, 0xbfb8aa3b, v137
	v_exp_f32_e32 v133, v133
	s_nop 0
	v_add_f32_e32 v133, 1.0, v133
	v_rcp_f32_e32 v139, v133
	s_nop 0
	v_pk_mul_f32 v[136:137], v[136:137], v[138:139]
	v_pk_mul_f32 v[138:139], v[40:41], v[134:135] op_sel_hi:[1,0]
	v_pk_mul_f32 v[136:137], v[140:141], v[136:137]
	v_mul_f32_e32 v133, 0xbfb8aa3b, v138
	v_exp_f32_e32 v133, v133
	s_nop 0
	v_add_f32_e32 v133, 1.0, v133
	v_rcp_f32_e32 v140, v133
	v_mul_f32_e32 v133, 0xbfb8aa3b, v139
	v_exp_f32_e32 v133, v133
	s_nop 0
	v_add_f32_e32 v133, 1.0, v133
	v_rcp_f32_e32 v141, v133
	s_nop 0
	v_pk_mul_f32 v[138:139], v[138:139], v[140:141]
	v_pk_mul_f32 v[140:141], v[34:35], v[134:135] op_sel_hi:[1,0]
	v_pk_mul_f32 v[138:139], v[142:143], v[138:139]
	v_mul_f32_e32 v133, 0xbfb8aa3b, v140
	v_exp_f32_e32 v133, v133
	s_nop 0
	v_add_f32_e32 v133, 1.0, v133
	v_rcp_f32_e32 v142, v133
	v_mul_f32_e32 v133, 0xbfb8aa3b, v141
	v_exp_f32_e32 v133, v133
	s_nop 0
	v_add_f32_e32 v133, 1.0, v133
	v_rcp_f32_e32 v143, v133
	s_nop 0
	v_pk_mul_f32 v[140:141], v[140:141], v[142:143]
	v_pk_mul_f32 v[142:143], v[36:37], v[134:135] op_sel_hi:[1,0]
	v_pk_mul_f32 v[140:141], v[144:145], v[140:141]
	v_mul_f32_e32 v133, 0xbfb8aa3b, v142
	v_exp_f32_e32 v133, v133
	v_pk_mul_f32 v[134:135], v[12:13], v[134:135] op_sel_hi:[1,0]
	v_add_f32_e32 v133, 1.0, v133
	v_rcp_f32_e32 v144, v133
	v_mul_f32_e32 v133, 0xbfb8aa3b, v143
	v_exp_f32_e32 v133, v133
	s_nop 0
	v_add_f32_e32 v133, 1.0, v133
	v_rcp_f32_e32 v145, v133
	s_nop 0
	v_pk_mul_f32 v[142:143], v[142:143], v[144:145]
	s_nop 0
	v_pk_mul_f32 v[142:143], v[134:135], v[142:143]
	v_cvt_pk_bf16_f32 v134, v136, v137
	v_cvt_pk_bf16_f32 v135, v138, v139
	v_cvt_pk_bf16_f32 v136, v140, v141
	v_cvt_pk_bf16_f32 v137, v142, v143
	v_mad_i64_i32 v[138:139], s[44:45], v166, s58, v[130:131]
	global_store_dwordx4 v[138:139], v[134:137], off
	v_mad_i64_i32 v[130:131], s[44:45], v164, s58, v[130:131]
	s_nop 0
	s_waitcnt lgkmcnt(0)
	v_pk_mul_f32 v[134:135], v[22:23], v[132:133] op_sel_hi:[1,0]
	s_nop 0
	v_mul_f32_e32 v133, 0xbfb8aa3b, v134
	v_exp_f32_e32 v133, v133
	s_nop 0
	v_add_f32_e32 v133, 1.0, v133
	v_rcp_f32_e32 v136, v133
	v_pk_mul_f32 v[138:139], v[6:7], v[132:133] op_sel_hi:[1,0]
	v_mul_f32_e32 v133, 0xbfb8aa3b, v135
	v_exp_f32_e32 v133, v133
	s_nop 0
	v_add_f32_e32 v133, 1.0, v133
	v_rcp_f32_e32 v137, v133
	s_nop 0
	v_pk_mul_f32 v[134:135], v[134:135], v[136:137]
	v_pk_mul_f32 v[136:137], v[24:25], v[132:133] op_sel_hi:[1,0]
	v_pk_mul_f32 v[134:135], v[138:139], v[134:135]
	v_mul_f32_e32 v133, 0xbfb8aa3b, v136
	v_exp_f32_e32 v133, v133
	s_nop 0
	v_add_f32_e32 v133, 1.0, v133
	v_rcp_f32_e32 v138, v133
	v_pk_mul_f32 v[140:141], v[8:9], v[132:133] op_sel_hi:[1,0]
	v_mul_f32_e32 v133, 0xbfb8aa3b, v137
	v_exp_f32_e32 v133, v133
	s_nop 0
	v_add_f32_e32 v133, 1.0, v133
	v_rcp_f32_e32 v139, v133
	s_nop 0
	v_pk_mul_f32 v[136:137], v[136:137], v[138:139]
	v_pk_mul_f32 v[138:139], v[18:19], v[132:133] op_sel_hi:[1,0]
	v_pk_mul_f32 v[136:137], v[140:141], v[136:137]
	v_mul_f32_e32 v133, 0xbfb8aa3b, v138
	v_exp_f32_e32 v133, v133
	s_nop 0
	v_add_f32_e32 v133, 1.0, v133
	v_rcp_f32_e32 v140, v133
	v_pk_mul_f32 v[142:143], v[2:3], v[132:133] op_sel_hi:[1,0]
	v_mul_f32_e32 v133, 0xbfb8aa3b, v139
	v_exp_f32_e32 v133, v133
	s_nop 0
	v_add_f32_e32 v133, 1.0, v133
	v_rcp_f32_e32 v141, v133
	s_nop 0
	v_pk_mul_f32 v[138:139], v[138:139], v[140:141]
	v_pk_mul_f32 v[140:141], v[20:21], v[132:133] op_sel_hi:[1,0]
	v_pk_mul_f32 v[138:139], v[142:143], v[138:139]
	v_mul_f32_e32 v133, 0xbfb8aa3b, v140
	v_mul_f32_e32 v143, 0xbfb8aa3b, v141
	v_exp_f32_e32 v133, v133
	v_exp_f32_e32 v143, v143
	v_add_f32_e32 v133, 1.0, v133
	v_add_f32_e32 v143, 1.0, v143
	v_rcp_f32_e32 v142, v133
	v_rcp_f32_e32 v143, v143
	v_pk_mul_f32 v[132:133], v[4:5], v[132:133] op_sel_hi:[1,0]
	v_pk_mul_f32 v[140:141], v[140:141], v[142:143]
	s_nop 0
	v_pk_mul_f32 v[140:141], v[132:133], v[140:141]
	v_cvt_pk_bf16_f32 v132, v134, v135
	v_cvt_pk_bf16_f32 v133, v136, v137
	v_cvt_pk_bf16_f32 v134, v138, v139
	v_cvt_pk_bf16_f32 v135, v140, v141
	global_store_dwordx4 v[130:131], v[132:135], off

; __device__ __forceinline__ void row_rstd8(const float* ssp, int row0, int fq, float (&rs)[2][4]) {
; #pragma unroll
;     for (int ai = 0; ai < 2; ++ai) {
;         f32x4 a[4], b[4];
; #pragma unroll
;         for (int m = 0; m < 4; ++m) { const float* q = ssp + (size_t)(row0 + ai * HALF + m * 16) * 32 + fq * 8; a[m] = *(const f32x4*)q; b[m] = *(const f32x4*)(q + 4); }
; #pragma unroll
;         for (int m = 0; m < 4; ++m) {
;             float s = ((a[m][0] + a[m][1]) + (a[m][2] + a[m][3])) + ((b[m][0] + b[m][1]) + (b[m][2] + b[m][3]));
;             s += __shfl_xor(s, 16); s += __shfl_xor(s, 32);
;             rs[ai][m] = rsqrtf(s * (1.0f / D) + 1e-6f);
;         }
;     }
; }
;     __device__ __forceinline__ void plain(const f32x4 (&acc)[2][2][4][2], bf16_t* base, int ld, int colbase, int row0, int cl) const {
;         const int fq = (cl >> 3) & 3;
;         const float* ssin = (const float*)(ws + OFF_SUMSQ) + (size_t)ssi * SS_SLOT;
;         float rsv[2][4];
;         row_rstd8(ssin, row0, fq, rsv);
.LBB0_596:
	v_cmp_lt_i32_e32 vcc, v232, v231
	v_ashrrev_i32_e32 v163, 31, v162
	v_or_b32_e32 v168, 16, v162
	v_cndmask_b32_e32 v130, v229, v232, vcc
	v_cmp_lt_i32_e32 vcc, v230, v231
	v_lshlrev_b32_e32 v173, 2, v130
	v_ashrrev_i32_e32 v169, 31, v168
	v_cndmask_b32_e32 v130, v229, v230, vcc
	v_lshlrev_b32_e32 v171, 2, v130
	s_waitcnt lgkmcnt(0)
	v_lshlrev_b64 v[130:131], 7, v[162:163]
	v_lshl_add_u64 v[134:135], v[190:191], 0, v[130:131]
	s_nop 0
	s_nop 0
	s_nop 0
	v_lshlrev_b64 v[138:139], 7, v[168:169]
	v_lshl_add_u64 v[142:143], v[190:191], 0, v[138:139]
	s_nop 0
	s_nop 0
	s_nop 0
	v_or_b32_e32 v166, 32, v162
	v_ashrrev_i32_e32 v167, 31, v166
	v_lshlrev_b64 v[146:147], 7, v[166:167]
	v_or_b32_e32 v164, 48, v162
	v_lshl_add_u64 v[150:151], v[190:191], 0, v[146:147]
	v_ashrrev_i32_e32 v165, 31, v164
	s_nop 0
	s_nop 0
	s_nop 0
	v_lshlrev_b64 v[154:155], 7, v[164:165]
	v_lshl_add_u64 v[158:159], v[190:191], 0, v[154:155]
	s_nop 0
	s_nop 0
	s_nop 0
	s_mov_b32 s30, 0x358637bd
	s_lshl_b64 s[44:45], s[44:45], 1
	v_mov_b64_e32 v[202:203], s[30:31]
	s_add_u32 s57, s26, s44
	s_addc_u32 s83, s27, s45
	v_add_u32_e32 v210, 0x80, v162
	v_ashrrev_i32_e32 v211, 31, v210
	v_add_u32_e32 v208, 0x90, v162
	v_ashrrev_i32_e32 v209, 31, v208
	v_add_u32_e32 v206, 0xa0, v162
	v_ashrrev_i32_e32 v207, 31, v206
	v_add_u32_e32 v204, 0xb0, v162
	v_ashrrev_i32_e32 v205, 31, v204
	s_ashr_i32 s61, s60, 31
	s_nop 0
	v_mov_b32_e32 v174, v130
	v_mov_b32_e32 v175, v134
	v_mov_b32_e32 v134, v131
	v_pk_add_f32 v[130:131], v[174:175], v[134:135]
	v_mov_b32_e32 v134, v132
	v_mov_b32_e32 v135, v136
	v_mov_b32_e32 v136, v133
	v_pk_add_f32 v[132:133], v[134:135], v[136:137]
	v_mov_b32_e32 v134, v140
	v_pk_add_f32 v[130:131], v[130:131], v[132:133]
	v_mov_b32_e32 v132, v138
	v_mov_b32_e32 v133, v142
	v_mov_b32_e32 v142, v139
	v_mov_b32_e32 v135, v144
	v_mov_b32_e32 v144, v141
	v_pk_add_f32 v[132:133], v[132:133], v[142:143]
	v_pk_add_f32 v[134:135], v[134:135], v[144:145]
	s_nop 0
	v_pk_add_f32 v[132:133], v[132:133], v[134:135]
	v_mov_b32_e32 v135, v130
	v_mov_b32_e32 v134, v132
	v_mov_b32_e32 v130, v133
	v_pk_add_f32 v[130:131], v[134:135], v[130:131]
	s_nop 0
	s_nop 0
	v_mov_b32_e32 v134, v156
	v_mov_b32_e32 v135, v160
	v_mov_b32_e32 v160, v157
	v_pk_add_f32 v[134:135], v[134:135], v[160:161]
	s_waitcnt lgkmcnt(0)
	v_pk_add_f32 v[130:131], v[130:131], v[132:133]
	s_nop 0
	s_nop 0
	s_waitcnt lgkmcnt(0)
	v_pk_add_f32 v[130:131], v[130:131], v[132:133]
	s_nop 0
	v_pk_fma_f32 v[130:131], v[130:131], s[22:23], v[202:203] op_sel_hi:[1,0,0]
	v_mov_b32_e32 v133, v152
	s_nop 0
	s_nop 0
	v_cmp_gt_f32_e32 vcc, s23, v130
	v_mov_b32_e32 v152, v149
	s_nop 0
	s_nop 0
	s_nop 0
	s_nop 0
	s_nop 0
	ds_read_b32 v176, v242 offset:0
	s_nop 0
	s_nop 0
	s_nop 0
	v_mov_b32_e32 v132, v148
	v_pk_add_f32 v[132:133], v[132:133], v[152:153]
	s_nop 0
	s_nop 0
	ds_read_b32 v174, v242 offset:64
	v_mov_b32_e32 v130, v146
	v_mov_b32_e32 v131, v150
	v_mov_b32_e32 v150, v147
	v_pk_add_f32 v[130:131], v[130:131], v[150:151]
	s_nop 0
	v_pk_add_f32 v[130:131], v[130:131], v[132:133]
	v_mov_b32_e32 v132, v154
	v_mov_b32_e32 v133, v158
	v_mov_b32_e32 v158, v155
	v_pk_add_f32 v[132:133], v[132:133], v[158:159]
	v_lshlrev_b64 v[154:155], 7, v[204:205]
	v_pk_add_f32 v[132:133], v[132:133], v[134:135]
	v_mov_b32_e32 v135, v130
	v_mov_b32_e32 v134, v132
	v_mov_b32_e32 v130, v133
	v_pk_add_f32 v[130:131], v[134:135], v[130:131]
	s_nop 0
	s_nop 0
	v_lshl_add_u64 v[154:155], v[190:191], 0, v[154:155]
	s_waitcnt lgkmcnt(0)
	v_pk_add_f32 v[130:131], v[130:131], v[132:133]
	s_nop 0
	s_nop 0
	s_waitcnt lgkmcnt(0)
	v_pk_add_f32 v[130:131], v[130:131], v[132:133]
	s_nop 0
	v_pk_fma_f32 v[130:131], v[130:131], s[22:23], v[202:203] op_sel_hi:[1,0,0]
	s_nop 0
	v_mul_f32_e32 v132, 0x4b800000, v131
	v_cmp_gt_f32_e64 s[44:45], s23, v131
	v_cmp_gt_f32_e32 vcc, s23, v130
	s_nop 0
	v_cndmask_b32_e64 v131, v131, v132, s[44:45]
	v_rsq_f32_e32 v131, v131
	s_nop 0
	v_mul_f32_e32 v132, 0x45800000, v131
	s_nop 0
	ds_read_b32 v172, v242 offset:128
	v_mul_f32_e32 v131, 0x4b800000, v130
	v_cndmask_b32_e32 v130, v130, v131, vcc
	v_rsq_f32_e32 v130, v130
	s_nop 0
	v_mul_f32_e32 v131, 0x45800000, v130
	s_nop 0
	ds_read_b32 v170, v242 offset:192
	v_lshlrev_b64 v[130:131], 7, v[210:211]
	v_lshl_add_u64 v[130:131], v[190:191], 0, v[130:131]
	s_nop 0
	s_nop 0
	v_lshlrev_b64 v[130:131], 7, v[208:209]
	v_lshl_add_u64 v[130:131], v[190:191], 0, v[130:131]
	s_nop 0
	s_nop 0
	v_lshlrev_b64 v[130:131], 7, v[206:207]
	v_lshl_add_u64 v[130:131], v[190:191], 0, v[130:131]
	s_nop 0
	s_nop 0
	s_nop 0
	s_nop 0
	s_nop 0
	s_nop 0
	s_nop 0
	s_nop 0
	v_mov_b32_e32 v212, v142
	s_nop 0
	v_mov_b32_e32 v213, v138
	v_mov_b32_e32 v138, v143
	v_mov_b32_e32 v142, v144
	v_mov_b32_e32 v143, v140
	v_mov_b32_e32 v140, v145
	v_pk_add_f32 v[138:139], v[212:213], v[138:139]
	v_pk_add_f32 v[140:141], v[142:143], v[140:141]
	s_nop 0
	v_mov_b32_e32 v142, v152
	v_pk_add_f32 v[138:139], v[138:139], v[140:141]
	v_mov_b32_e32 v140, v150
	s_nop 0
	v_mov_b32_e32 v141, v146
	v_mov_b32_e32 v146, v151
	v_mov_b32_e32 v143, v148
	v_mov_b32_e32 v148, v153
	v_pk_add_f32 v[140:141], v[140:141], v[146:147]
	v_pk_add_f32 v[142:143], v[142:143], v[148:149]
	s_waitcnt lgkmcnt(0)
; __device__ __forceinline__ unsigned cvt_pk_bf16(float lo, float hi) { const f32x2_t v = {lo, hi}; return __builtin_bit_cast(unsigned, __builtin_convertvector(v, bf16x2_t)); }
; __device__ __forceinline__ void row_rstd8(const float* ssp, int row0, int fq, float (&rs)[2][4]) {
;     ...
;         for (int m = 0; m < 4; ++m) {
;             float s = ((a[m][0] + a[m][1]) + (a[m][2] + a[m][3])) + ((b[m][0] + b[m][1]) + (b[m][2] + b[m][3]));
;             s += __shfl_xor(s, 16); s += __shfl_xor(s, 32);
;             rs[ai][m] = rsqrtf(s * (1.0f / D) + 1e-6f);
;         }
;     __device__ __forceinline__ void plain(const f32x4 (&acc)[2][2][4][2], bf16_t* base, int ld, int colbase, int row0, int cl) const {
;     ...
; #pragma unroll
;         for (int ai = 0; ai < 2; ++ai)
; #pragma unroll
;             for (int m = 0; m < 4; ++m) {
;                 const int row = row0 + ai * HALF + m * 16;
;                 const float rs = rsv[ai][m];
;                 bf16_t* rp = base + (size_t)row * ld + colbase + cl;
; #pragma unroll
;                 for (int bj = 0; bj < 2; ++bj) {
;                     const f32x4 v0 = acc[ai][bj][m][0] * rs, v1 = acc[ai][bj][m][1] * rs;
;                     u32x4 w; w.x = cvt_pk_bf16(v0[0], v0[1]); w.y = cvt_pk_bf16(v0[2], v0[3]); w.z = cvt_pk_bf16(v1[0], v1[1]); w.w = cvt_pk_bf16(v1[2], v1[3]);
;                     *(u32x4*)(rp + bj * HALF) = w;
;                 }
;             }
	v_pk_mul_f32 v[144:145], v[128:129], v[176:177] op_sel_hi:[1,0]
	v_pk_add_f32 v[140:141], v[140:141], v[142:143]
	v_mov_b32_e32 v143, v138
	v_mov_b32_e32 v142, v140
	v_mov_b32_e32 v138, v141
	v_pk_add_f32 v[138:139], v[142:143], v[138:139]
	s_nop 0
	s_nop 0
	s_nop 0
	v_mov_b32_e32 v142, v134
	s_nop 0
	v_mov_b32_e32 v143, v130
	v_mov_b32_e32 v130, v135
	v_mov_b32_e32 v134, v136
	v_mov_b32_e32 v135, v132
	v_mov_b32_e32 v132, v137
	v_pk_add_f32 v[130:131], v[142:143], v[130:131]
	v_pk_add_f32 v[132:133], v[134:135], v[132:133]
	s_nop 0
	v_mov_b32_e32 v134, v160
	v_pk_add_f32 v[130:131], v[130:131], v[132:133]
	v_mov_b32_e32 v132, v158
	s_nop 0
	v_mov_b32_e32 v133, v154
	v_mov_b32_e32 v154, v159
	v_mov_b32_e32 v135, v156
	v_mov_b32_e32 v156, v161
	v_pk_add_f32 v[132:133], v[132:133], v[154:155]
	v_pk_add_f32 v[134:135], v[134:135], v[156:157]
	s_waitcnt lgkmcnt(0)
	v_pk_add_f32 v[138:139], v[138:139], v[140:141]
	v_pk_add_f32 v[132:133], v[132:133], v[134:135]
	v_mov_b32_e32 v135, v130
	v_mov_b32_e32 v134, v132
	v_mov_b32_e32 v130, v133
	s_nop 0
	s_nop 0
	v_pk_add_f32 v[130:131], v[134:135], v[130:131]
	s_nop 0
	s_nop 0
	v_pk_mul_f32 v[142:143], v[126:127], v[176:177] op_sel_hi:[1,0]
	s_waitcnt lgkmcnt(2)
	v_pk_add_f32 v[138:139], v[138:139], v[140:141]
	v_pk_mul_f32 v[146:147], v[124:125], v[176:177] op_sel_hi:[1,0]
	v_pk_fma_f32 v[138:139], v[138:139], s[22:23], v[202:203] op_sel_hi:[1,0,0]
	s_waitcnt lgkmcnt(0)
	v_pk_add_f32 v[130:131], v[130:131], v[132:133]
	s_nop 0
	s_nop 0
	s_nop 0
	s_nop 0
	s_nop 0
	s_nop 0
	v_pk_mul_f32 v[148:149], v[122:123], v[176:177] op_sel_hi:[1,0]
	v_cvt_pk_bf16_f32 v142, v142, v143
	s_waitcnt lgkmcnt(0)
	v_pk_add_f32 v[130:131], v[130:131], v[132:133]
	s_nop 0
	v_pk_fma_f32 v[130:131], v[130:131], s[22:23], v[202:203] op_sel_hi:[1,0,0]
	s_nop 0
	ds_read_b32 v140, v242 offset:512
	s_nop 0
	v_cmp_gt_f32_e64 s[44:45], s23, v131
	v_cvt_pk_bf16_f32 v143, v144, v145
	v_cvt_pk_bf16_f32 v144, v148, v149
	s_nop 0
	s_nop 0
	v_cvt_pk_bf16_f32 v145, v146, v147
	v_pk_mul_f32 v[146:147], v[108:109], v[176:177] op_sel_hi:[1,0]
	v_pk_mul_f32 v[148:149], v[106:107], v[176:177] op_sel_hi:[1,0]
	s_nop 0
	s_nop 0
	ds_read_b32 v132, v242 offset:640
	s_lshl_b64 s[44:45], s[60:61], 1
	s_add_u32 s44, s57, s44
	s_addc_u32 s45, s83, s45
	v_lshl_add_u64 v[134:135], s[44:45], 0, v[0:1]
	v_mad_i64_i32 v[136:137], s[44:45], s56, v162, 0
	v_lshl_add_u64 v[136:137], v[136:137], 1, v[134:135]
	global_store_dwordx4 v[136:137], v[142:145], off
	v_cmp_gt_f32_e32 vcc, s23, v138
	v_mul_f32_e32 v139, 0x4b800000, v138
	v_pk_mul_f32 v[144:145], v[116:117], v[176:177] op_sel_hi:[1,0]
	v_pk_mul_f32 v[142:143], v[114:115], v[176:177] op_sel_hi:[1,0]
	v_cndmask_b32_e32 v138, v138, v139, vcc
	v_cvt_pk_bf16_f32 v142, v142, v143
	v_cvt_pk_bf16_f32 v143, v144, v145
	v_cvt_pk_bf16_f32 v144, v148, v149
	v_cvt_pk_bf16_f32 v145, v146, v147
	global_store_dwordx4 v[136:137], v[142:145], off offset:256
	v_mad_i64_i32 v[136:137], s[44:45], s56, v168, 0
	s_nop 0
	s_waitcnt lgkmcnt(0)
	v_pk_mul_f32 v[144:145], v[120:121], v[174:175] op_sel_hi:[1,0]
	v_pk_mul_f32 v[142:143], v[118:119], v[174:175] op_sel_hi:[1,0]
	v_pk_mul_f32 v[146:147], v[112:113], v[174:175] op_sel_hi:[1,0]
	v_pk_mul_f32 v[148:149], v[110:111], v[174:175] op_sel_hi:[1,0]
	v_lshl_add_u64 v[136:137], v[136:137], 1, v[134:135]
	v_cvt_pk_bf16_f32 v142, v142, v143
	v_cvt_pk_bf16_f32 v143, v144, v145
	v_cvt_pk_bf16_f32 v144, v148, v149
	v_cvt_pk_bf16_f32 v145, v146, v147
	global_store_dwordx4 v[136:137], v[142:145], off
	v_pk_mul_f32 v[146:147], v[92:93], v[174:175] op_sel_hi:[1,0]
	v_pk_mul_f32 v[148:149], v[90:91], v[174:175] op_sel_hi:[1,0]
	v_pk_mul_f32 v[144:145], v[100:101], v[174:175] op_sel_hi:[1,0]
	v_pk_mul_f32 v[142:143], v[98:99], v[174:175] op_sel_hi:[1,0]
	v_rsq_f32_e32 v138, v138
	v_cvt_pk_bf16_f32 v142, v142, v143
	v_cvt_pk_bf16_f32 v143, v144, v145
	v_cvt_pk_bf16_f32 v144, v148, v149
	v_cvt_pk_bf16_f32 v145, v146, v147
	global_store_dwordx4 v[136:137], v[142:145], off offset:256
	v_mad_i64_i32 v[136:137], s[44:45], s56, v166, 0
	s_nop 0
	s_waitcnt lgkmcnt(0)
	v_pk_mul_f32 v[144:145], v[104:105], v[172:173] op_sel_hi:[1,0]
	v_pk_mul_f32 v[142:143], v[102:103], v[172:173] op_sel_hi:[1,0]
	v_pk_mul_f32 v[146:147], v[96:97], v[172:173] op_sel_hi:[1,0]
	v_pk_mul_f32 v[148:149], v[94:95], v[172:173] op_sel_hi:[1,0]
	v_lshl_add_u64 v[136:137], v[136:137], 1, v[134:135]
	v_cvt_pk_bf16_f32 v142, v142, v143
	v_cvt_pk_bf16_f32 v143, v144, v145
	v_cvt_pk_bf16_f32 v144, v148, v149
	v_cvt_pk_bf16_f32 v145, v146, v147
	global_store_dwordx4 v[136:137], v[142:145], off
	v_pk_mul_f32 v[146:147], v[76:77], v[172:173] op_sel_hi:[1,0]
	v_pk_mul_f32 v[148:149], v[74:75], v[172:173] op_sel_hi:[1,0]
	v_pk_mul_f32 v[144:145], v[84:85], v[172:173] op_sel_hi:[1,0]
	v_pk_mul_f32 v[142:143], v[82:83], v[172:173] op_sel_hi:[1,0]
	v_mul_f32_e32 v139, 0x45800000, v138
	v_cvt_pk_bf16_f32 v142, v142, v143
	v_cvt_pk_bf16_f32 v143, v144, v145
	v_cvt_pk_bf16_f32 v144, v148, v149
	v_cvt_pk_bf16_f32 v145, v146, v147
	global_store_dwordx4 v[136:137], v[142:145], off offset:256
	v_mad_i64_i32 v[136:137], s[44:45], s56, v164, 0
	s_nop 0
	s_waitcnt lgkmcnt(0)
; __device__ __forceinline__ unsigned cvt_pk_bf16(float lo, float hi) { const f32x2_t v = {lo, hi}; return __builtin_bit_cast(unsigned, __builtin_convertvector(v, bf16x2_t)); }
;     __device__ __forceinline__ void plain(const f32x4 (&acc)[2][2][4][2], bf16_t* base, int ld, int colbase, int row0, int cl) const {
;     ...
; #pragma unroll
;         for (int ai = 0; ai < 2; ++ai)
; #pragma unroll
;             for (int m = 0; m < 4; ++m) {
;                 const int row = row0 + ai * HALF + m * 16;
;                 const float rs = rsv[ai][m];
;                 bf16_t* rp = base + (size_t)row * ld + colbase + cl;
; #pragma unroll
;                 for (int bj = 0; bj < 2; ++bj) {
;                     const f32x4 v0 = acc[ai][bj][m][0] * rs, v1 = acc[ai][bj][m][1] * rs;
;                     u32x4 w; w.x = cvt_pk_bf16(v0[0], v0[1]); w.y = cvt_pk_bf16(v0[2], v0[3]); w.z = cvt_pk_bf16(v1[0], v1[1]); w.w = cvt_pk_bf16(v1[2], v1[3]);
;                     *(u32x4*)(rp + bj * HALF) = w;
;                 }
;             }
	v_pk_mul_f32 v[144:145], v[88:89], v[170:171] op_sel_hi:[1,0]
	v_pk_mul_f32 v[142:143], v[86:87], v[170:171] op_sel_hi:[1,0]
	v_pk_mul_f32 v[146:147], v[80:81], v[170:171] op_sel_hi:[1,0]
	v_pk_mul_f32 v[148:149], v[78:79], v[170:171] op_sel_hi:[1,0]
	v_lshl_add_u64 v[136:137], v[136:137], 1, v[134:135]
	v_cvt_pk_bf16_f32 v142, v142, v143
	v_cvt_pk_bf16_f32 v143, v144, v145
	v_cvt_pk_bf16_f32 v144, v148, v149
	v_cvt_pk_bf16_f32 v145, v146, v147
	global_store_dwordx4 v[136:137], v[142:145], off
	v_pk_mul_f32 v[146:147], v[68:69], v[170:171] op_sel_hi:[1,0]
	v_pk_mul_f32 v[148:149], v[66:67], v[170:171] op_sel_hi:[1,0]
	v_pk_mul_f32 v[144:145], v[72:73], v[170:171] op_sel_hi:[1,0]
	v_pk_mul_f32 v[142:143], v[70:71], v[170:171] op_sel_hi:[1,0]
	s_nop 0
	ds_read_b32 v138, v242 offset:576
	v_cvt_pk_bf16_f32 v142, v142, v143
	v_cvt_pk_bf16_f32 v143, v144, v145
	v_cvt_pk_bf16_f32 v144, v148, v149
	v_cvt_pk_bf16_f32 v145, v146, v147
	global_store_dwordx4 v[136:137], v[142:145], off offset:256
	v_mad_i64_i32 v[136:137], s[44:45], s56, v210, 0
	s_nop 0
	s_waitcnt lgkmcnt(0)
	v_pk_mul_f32 v[144:145], v[64:65], v[140:141] op_sel_hi:[1,0]
	v_pk_mul_f32 v[142:143], v[62:63], v[140:141] op_sel_hi:[1,0]
	v_pk_mul_f32 v[146:147], v[60:61], v[140:141] op_sel_hi:[1,0]
	v_pk_mul_f32 v[148:149], v[58:59], v[140:141] op_sel_hi:[1,0]
	v_lshl_add_u64 v[136:137], v[136:137], 1, v[134:135]
	v_cvt_pk_bf16_f32 v142, v142, v143
	v_cvt_pk_bf16_f32 v143, v144, v145
	v_cvt_pk_bf16_f32 v144, v148, v149
	v_cvt_pk_bf16_f32 v145, v146, v147
	global_store_dwordx4 v[136:137], v[142:145], off
	v_pk_mul_f32 v[146:147], v[44:45], v[140:141] op_sel_hi:[1,0]
	v_pk_mul_f32 v[148:149], v[42:43], v[140:141] op_sel_hi:[1,0]
	v_pk_mul_f32 v[142:143], v[48:49], v[140:141] op_sel_hi:[1,0]
	v_pk_mul_f32 v[144:145], v[46:47], v[140:141] op_sel_hi:[1,0]
	v_cvt_pk_bf16_f32 v141, v142, v143
	v_cvt_pk_bf16_f32 v140, v144, v145
	v_cvt_pk_bf16_f32 v142, v148, v149
	v_cvt_pk_bf16_f32 v143, v146, v147
	global_store_dwordx4 v[136:137], v[140:143], off offset:256
	v_mad_i64_i32 v[136:137], s[44:45], s56, v208, 0
	v_lshl_add_u64 v[144:145], v[136:137], 1, v[134:135]
	s_waitcnt lgkmcnt(0)
	v_pk_mul_f32 v[136:137], v[56:57], v[138:139] op_sel_hi:[1,0]
	v_pk_mul_f32 v[140:141], v[54:55], v[138:139] op_sel_hi:[1,0]
	v_pk_mul_f32 v[146:147], v[52:53], v[138:139] op_sel_hi:[1,0]
	v_pk_mul_f32 v[142:143], v[50:51], v[138:139] op_sel_hi:[1,0]
	v_cmp_gt_f32_e32 vcc, s23, v130
	v_mul_f32_e32 v131, 0x4b800000, v130
	v_cvt_pk_bf16_f32 v140, v140, v141
	v_cvt_pk_bf16_f32 v141, v136, v137
	v_cvt_pk_bf16_f32 v142, v142, v143
	v_cvt_pk_bf16_f32 v143, v146, v147
	v_cndmask_b32_e32 v130, v130, v131, vcc
	global_store_dwordx4 v[144:145], v[140:143], off
	v_pk_mul_f32 v[136:137], v[30:31], v[138:139] op_sel_hi:[1,0]
	v_rsq_f32_e32 v130, v130
	v_pk_mul_f32 v[140:141], v[32:33], v[138:139] op_sel_hi:[1,0]
	v_pk_mul_f32 v[142:143], v[28:29], v[138:139] op_sel_hi:[1,0]
	v_pk_mul_f32 v[138:139], v[26:27], v[138:139] op_sel_hi:[1,0]
	v_cvt_pk_bf16_f32 v136, v136, v137
	v_cvt_pk_bf16_f32 v137, v140, v141
	v_cvt_pk_bf16_f32 v138, v138, v139
	v_cvt_pk_bf16_f32 v139, v142, v143
	global_store_dwordx4 v[144:145], v[136:139], off offset:256
	s_waitcnt lgkmcnt(0)
	v_pk_mul_f32 v[142:143], v[36:37], v[132:133] op_sel_hi:[1,0]
	v_pk_mul_f32 v[144:145], v[34:35], v[132:133] op_sel_hi:[1,0]
	v_mad_i64_i32 v[136:137], s[44:45], s56, v206, 0
	v_lshl_add_u64 v[140:141], v[136:137], 1, v[134:135]
	v_pk_mul_f32 v[138:139], v[40:41], v[132:133] op_sel_hi:[1,0]
	v_pk_mul_f32 v[136:137], v[38:39], v[132:133] op_sel_hi:[1,0]
	v_mul_f32_e32 v131, 0x45800000, v130
	v_cvt_pk_bf16_f32 v136, v136, v137
	v_cvt_pk_bf16_f32 v137, v138, v139
	v_cvt_pk_bf16_f32 v138, v144, v145
	v_cvt_pk_bf16_f32 v139, v142, v143
	global_store_dwordx4 v[140:141], v[136:139], off
	v_pk_mul_f32 v[142:143], v[12:13], v[132:133] op_sel_hi:[1,0]
	s_nop 0
	ds_read_b32 v130, v242 offset:704
	v_pk_mul_f32 v[138:139], v[16:17], v[132:133] op_sel_hi:[1,0]
	v_pk_mul_f32 v[136:137], v[14:15], v[132:133] op_sel_hi:[1,0]
	v_pk_mul_f32 v[132:133], v[10:11], v[132:133] op_sel_hi:[1,0]
	v_cvt_pk_bf16_f32 v136, v136, v137
	v_cvt_pk_bf16_f32 v137, v138, v139
	v_cvt_pk_bf16_f32 v138, v132, v133
	v_cvt_pk_bf16_f32 v139, v142, v143
	v_mad_i64_i32 v[132:133], s[44:45], s56, v204, 0
	global_store_dwordx4 v[140:141], v[136:139], off offset:256
	s_waitcnt lgkmcnt(0)
	v_pk_mul_f32 v[140:141], v[18:19], v[130:131] op_sel_hi:[1,0]
	s_nop 0
	v_lshl_add_u64 v[136:137], v[132:133], 1, v[134:135]
	v_pk_mul_f32 v[134:135], v[24:25], v[130:131] op_sel_hi:[1,0]
	v_pk_mul_f32 v[132:133], v[22:23], v[130:131] op_sel_hi:[1,0]
	v_pk_mul_f32 v[138:139], v[20:21], v[130:131] op_sel_hi:[1,0]
	v_cvt_pk_bf16_f32 v132, v132, v133
	v_cvt_pk_bf16_f32 v133, v134, v135
	v_cvt_pk_bf16_f32 v134, v140, v141
	v_cvt_pk_bf16_f32 v135, v138, v139
	global_store_dwordx4 v[136:137], v[132:135], off
	v_pk_mul_f32 v[138:139], v[4:5], v[130:131] op_sel_hi:[1,0]
	v_pk_mul_f32 v[140:141], v[2:3], v[130:131] op_sel_hi:[1,0]
	v_pk_mul_f32 v[132:133], v[8:9], v[130:131] op_sel_hi:[1,0]
	v_pk_mul_f32 v[134:135], v[6:7], v[130:131] op_sel_hi:[1,0]
	v_cvt_pk_bf16_f32 v131, v132, v133
	v_cvt_pk_bf16_f32 v130, v134, v135
	v_cvt_pk_bf16_f32 v132, v140, v141
	v_cvt_pk_bf16_f32 v133, v138, v139
	global_store_dwordx4 v[136:137], v[130:133], off offset:256

; __device__ __forceinline__ void row_rstd8(const float* ssp, int row0, int fq, float (&rs)[2][4]) {
; #pragma unroll
;     for (int ai = 0; ai < 2; ++ai) {
;         f32x4 a[4], b[4];
; #pragma unroll
;         for (int m = 0; m < 4; ++m) { const float* q = ssp + (size_t)(row0 + ai * HALF + m * 16) * 32 + fq * 8; a[m] = *(const f32x4*)q; b[m] = *(const f32x4*)(q + 4); }
; #pragma unroll
;         for (int m = 0; m < 4; ++m) {
;             float s = ((a[m][0] + a[m][1]) + (a[m][2] + a[m][3])) + ((b[m][0] + b[m][1]) + (b[m][2] + b[m][3]));
;             s += __shfl_xor(s, 16); s += __shfl_xor(s, 32);
;             rs[ai][m] = rsqrtf(s * (1.0f / D) + 1e-6f);
;         }
;     }
; }
;     __device__ __forceinline__ void plain(const f32x4 (&acc)[2][2][4][2], bf16_t* base, int ld, int colbase, int row0, int cl) const {
;         const int fq = (cl >> 3) & 3;
;         const float* ssin = (const float*)(ws + OFF_SUMSQ) + (size_t)ssi * SS_SLOT;
;         float rsv[2][4];
;         row_rstd8(ssin, row0, fq, rsv);
.LBB0_616:
	s_and_b64 vcc, exec, s[44:45]
	s_cbranch_vccz .LBB0_618
	v_ashrrev_i32_e32 v163, 31, v162
	s_waitcnt lgkmcnt(0)
	v_lshlrev_b64 v[130:131], 7, v[162:163]
	v_lshl_add_u64 v[134:135], v[190:191], 0, v[130:131]
	v_or_b32_e32 v168, 16, v162
	s_nop 0
	s_nop 0
	s_nop 0
	v_ashrrev_i32_e32 v169, 31, v168
	v_lshlrev_b64 v[138:139], 7, v[168:169]
	v_lshl_add_u64 v[142:143], v[190:191], 0, v[138:139]
	s_nop 0
	s_nop 0
	s_nop 0
	v_or_b32_e32 v166, 32, v162
	v_ashrrev_i32_e32 v167, 31, v166
	v_lshlrev_b64 v[146:147], 7, v[166:167]
	v_or_b32_e32 v164, 48, v162
	v_lshl_add_u64 v[150:151], v[190:191], 0, v[146:147]
	v_ashrrev_i32_e32 v165, 31, v164
	s_nop 0
	s_nop 0
	s_nop 0
	v_lshlrev_b64 v[154:155], 7, v[164:165]
	v_lshl_add_u64 v[158:159], v[190:191], 0, v[154:155]
	s_nop 0
	s_nop 0
	s_nop 0
	s_mov_b32 s30, 0x358637bd
	v_mov_b64_e32 v[202:203], s[30:31]
	v_add_u32_e32 v210, 0x80, v162
	v_ashrrev_i32_e32 v211, 31, v210
	v_add_u32_e32 v208, 0x90, v162
	v_ashrrev_i32_e32 v209, 31, v208
	v_add_u32_e32 v206, 0xa0, v162
	v_ashrrev_i32_e32 v207, 31, v206
	v_add_u32_e32 v204, 0xb0, v162
	v_ashrrev_i32_e32 v205, 31, v204
	s_lshl_b32 s56, s82, 8
	s_ashr_i32 s57, s56, 31
	s_nop 0
	v_mov_b32_e32 v174, v130
	v_mov_b32_e32 v175, v134
	v_mov_b32_e32 v134, v131
	v_pk_add_f32 v[130:131], v[174:175], v[134:135]
	v_mov_b32_e32 v134, v132
	v_mov_b32_e32 v135, v136
	v_mov_b32_e32 v136, v133
	v_pk_add_f32 v[132:133], v[134:135], v[136:137]
	v_mov_b32_e32 v134, v140
	v_pk_add_f32 v[130:131], v[130:131], v[132:133]
	v_mov_b32_e32 v132, v138
	v_mov_b32_e32 v133, v142
	v_mov_b32_e32 v142, v139
	v_mov_b32_e32 v135, v144
	v_mov_b32_e32 v144, v141
	v_pk_add_f32 v[132:133], v[132:133], v[142:143]
	v_pk_add_f32 v[134:135], v[134:135], v[144:145]
	s_nop 0
	v_pk_add_f32 v[132:133], v[132:133], v[134:135]
	v_mov_b32_e32 v135, v130
	v_mov_b32_e32 v134, v132
	v_mov_b32_e32 v130, v133
	v_pk_add_f32 v[130:131], v[134:135], v[130:131]
	s_nop 0
	s_nop 0
	v_mov_b32_e32 v134, v156
	v_mov_b32_e32 v135, v160
	v_mov_b32_e32 v160, v157
	v_pk_add_f32 v[134:135], v[134:135], v[160:161]
	s_waitcnt lgkmcnt(0)
	v_pk_add_f32 v[130:131], v[130:131], v[132:133]
	s_nop 0
	s_nop 0
	s_waitcnt lgkmcnt(0)
	v_pk_add_f32 v[130:131], v[130:131], v[132:133]
	s_nop 0
	v_pk_fma_f32 v[130:131], v[130:131], s[22:23], v[202:203] op_sel_hi:[1,0,0]
	v_mov_b32_e32 v133, v152
	s_nop 0
	s_nop 0
	v_cmp_gt_f32_e32 vcc, s23, v130
	v_mov_b32_e32 v152, v149
	s_nop 0
	s_nop 0
	s_nop 0
	s_nop 0
	s_nop 0
	ds_read_b32 v176, v242 offset:0
	s_nop 0
	s_nop 0
	s_nop 0
	v_mov_b32_e32 v132, v148
	v_pk_add_f32 v[132:133], v[132:133], v[152:153]
	s_nop 0
	s_nop 0
	ds_read_b32 v172, v242 offset:64
	v_mov_b32_e32 v130, v146
	v_mov_b32_e32 v131, v150
	v_mov_b32_e32 v150, v147
	v_pk_add_f32 v[130:131], v[130:131], v[150:151]
	v_lshlrev_b64 v[146:147], 7, v[204:205]
	v_pk_add_f32 v[130:131], v[130:131], v[132:133]
	v_mov_b32_e32 v132, v154
	v_mov_b32_e32 v133, v158
	v_mov_b32_e32 v158, v155
	v_pk_add_f32 v[132:133], v[132:133], v[158:159]
	v_lshl_add_u64 v[146:147], v[190:191], 0, v[146:147]
	v_pk_add_f32 v[132:133], v[132:133], v[134:135]
	v_mov_b32_e32 v135, v130
	v_mov_b32_e32 v134, v132
	v_mov_b32_e32 v130, v133
	v_pk_add_f32 v[130:131], v[134:135], v[130:131]
	s_nop 0
	s_nop 0
	s_waitcnt lgkmcnt(0)
	v_pk_add_f32 v[130:131], v[130:131], v[132:133]
	s_nop 0
	s_nop 0
	s_waitcnt lgkmcnt(0)
	v_pk_add_f32 v[130:131], v[130:131], v[132:133]
	s_nop 0
	v_pk_fma_f32 v[130:131], v[130:131], s[22:23], v[202:203] op_sel_hi:[1,0,0]
	s_nop 0
	v_mul_f32_e32 v132, 0x4b800000, v131
	v_cmp_gt_f32_e64 s[44:45], s23, v131
	v_cmp_gt_f32_e32 vcc, s23, v130
	s_nop 0
	v_cndmask_b32_e64 v131, v131, v132, s[44:45]
	v_rsq_f32_e32 v131, v131
	s_nop 0
	v_mul_f32_e32 v132, 0x45800000, v131
	s_nop 0
	ds_read_b32 v174, v242 offset:128
	v_mul_f32_e32 v131, 0x4b800000, v130
	v_cndmask_b32_e32 v130, v130, v131, vcc
	v_rsq_f32_e32 v130, v130
	s_nop 0
	v_mul_f32_e32 v131, 0x45800000, v130
	s_nop 0
	ds_read_b32 v170, v242 offset:192
	v_lshlrev_b64 v[130:131], 7, v[210:211]
	v_lshl_add_u64 v[130:131], v[190:191], 0, v[130:131]
	s_nop 0
	s_nop 0
	v_lshlrev_b64 v[130:131], 7, v[208:209]
	v_lshl_add_u64 v[130:131], v[190:191], 0, v[130:131]
	s_nop 0
	s_nop 0
	v_lshlrev_b64 v[130:131], 7, v[206:207]
	v_lshl_add_u64 v[130:131], v[190:191], 0, v[130:131]
	s_nop 0
	s_nop 0
	s_nop 0
	s_nop 0
	s_nop 0
	s_nop 0
	s_nop 0
	s_nop 0
	v_mov_b32_e32 v212, v142
	s_nop 0
	v_mov_b32_e32 v213, v138
	v_mov_b32_e32 v138, v143
	v_mov_b32_e32 v142, v144
	v_mov_b32_e32 v143, v140
	v_mov_b32_e32 v140, v145
	v_pk_add_f32 v[138:139], v[212:213], v[138:139]
	v_pk_add_f32 v[140:141], v[142:143], v[140:141]
	s_nop 0
	v_mov_b32_e32 v142, v160
	v_pk_add_f32 v[138:139], v[138:139], v[140:141]
	v_mov_b32_e32 v140, v158
	s_nop 0
	v_mov_b32_e32 v141, v154
	v_mov_b32_e32 v154, v159
	v_mov_b32_e32 v143, v156
	v_mov_b32_e32 v156, v161
	v_pk_add_f32 v[140:141], v[140:141], v[154:155]
	v_pk_add_f32 v[142:143], v[142:143], v[156:157]
	s_waitcnt lgkmcnt(0)
	v_pk_mul_f32 v[144:145], v[128:129], v[176:177] op_sel_hi:[1,0]
	v_pk_add_f32 v[140:141], v[140:141], v[142:143]
	v_mov_b32_e32 v143, v138
	v_mov_b32_e32 v142, v140
	v_mov_b32_e32 v138, v141
	v_pk_add_f32 v[138:139], v[142:143], v[138:139]
	s_nop 0
	s_nop 0
	s_nop 0
	v_mov_b32_e32 v142, v134
	s_nop 0
	v_mov_b32_e32 v143, v130
	v_mov_b32_e32 v130, v135
	v_mov_b32_e32 v134, v136
	v_mov_b32_e32 v135, v132
	v_mov_b32_e32 v132, v137
	v_pk_add_f32 v[130:131], v[142:143], v[130:131]
	v_pk_add_f32 v[132:133], v[134:135], v[132:133]
	s_nop 0
	v_mov_b32_e32 v134, v152
	v_pk_add_f32 v[130:131], v[130:131], v[132:133]
	v_mov_b32_e32 v132, v150
	s_nop 0
	v_mov_b32_e32 v133, v146
	v_mov_b32_e32 v146, v151
	v_mov_b32_e32 v135, v148
	v_mov_b32_e32 v148, v153
	v_pk_add_f32 v[132:133], v[132:133], v[146:147]
	v_pk_add_f32 v[134:135], v[134:135], v[148:149]
	s_waitcnt lgkmcnt(0)
; __device__ __forceinline__ unsigned cvt_pk_bf16(float lo, float hi) { const f32x2_t v = {lo, hi}; return __builtin_bit_cast(unsigned, __builtin_convertvector(v, bf16x2_t)); }
; __device__ __forceinline__ void row_rstd8(const float* ssp, int row0, int fq, float (&rs)[2][4]) {
;     ...
;         for (int m = 0; m < 4; ++m) {
;             float s = ((a[m][0] + a[m][1]) + (a[m][2] + a[m][3])) + ((b[m][0] + b[m][1]) + (b[m][2] + b[m][3]));
;             s += __shfl_xor(s, 16); s += __shfl_xor(s, 32);
;             rs[ai][m] = rsqrtf(s * (1.0f / D) + 1e-6f);
;         }
;     __device__ __forceinline__ void plain(const f32x4 (&acc)[2][2][4][2], bf16_t* base, int ld, int colbase, int row0, int cl) const {
;     ...
; #pragma unroll
;         for (int ai = 0; ai < 2; ++ai)
; #pragma unroll
;             for (int m = 0; m < 4; ++m) {
;                 const int row = row0 + ai * HALF + m * 16;
;                 const float rs = rsv[ai][m];
;                 bf16_t* rp = base + (size_t)row * ld + colbase + cl;
; #pragma unroll
;                 for (int bj = 0; bj < 2; ++bj) {
;                     const f32x4 v0 = acc[ai][bj][m][0] * rs, v1 = acc[ai][bj][m][1] * rs;
;                     u32x4 w; w.x = cvt_pk_bf16(v0[0], v0[1]); w.y = cvt_pk_bf16(v0[2], v0[3]); w.z = cvt_pk_bf16(v1[0], v1[1]); w.w = cvt_pk_bf16(v1[2], v1[3]);
;                     *(u32x4*)(rp + bj * HALF) = w;
;                 }
;             }
	v_pk_add_f32 v[138:139], v[138:139], v[140:141]
	v_pk_add_f32 v[132:133], v[132:133], v[134:135]
	v_mov_b32_e32 v135, v130
	v_mov_b32_e32 v134, v132
	v_mov_b32_e32 v130, v133
	s_nop 0
	s_nop 0
	v_pk_add_f32 v[130:131], v[134:135], v[130:131]
	s_nop 0
	s_nop 0
	v_lshl_add_u64 v[134:135], s[56:57], 1, v[188:189]
	s_waitcnt lgkmcnt(2)
	v_pk_add_f32 v[138:139], v[138:139], v[140:141]
	v_pk_mul_f32 v[142:143], v[126:127], v[176:177] op_sel_hi:[1,0]
	v_pk_fma_f32 v[138:139], v[138:139], s[22:23], v[202:203] op_sel_hi:[1,0,0]
	s_waitcnt lgkmcnt(0)
	v_pk_add_f32 v[130:131], v[130:131], v[132:133]
	s_nop 0
	s_nop 0
	s_nop 0
	s_nop 0
	s_nop 0
	s_nop 0
	v_pk_mul_f32 v[146:147], v[124:125], v[176:177] op_sel_hi:[1,0]
	v_pk_mul_f32 v[148:149], v[122:123], v[176:177] op_sel_hi:[1,0]
	s_waitcnt lgkmcnt(0)
	v_pk_add_f32 v[130:131], v[130:131], v[132:133]
	s_nop 0
	v_pk_fma_f32 v[130:131], v[130:131], s[22:23], v[202:203] op_sel_hi:[1,0,0]
	s_nop 0
	ds_read_b32 v140, v242 offset:512
	s_nop 0
	v_cmp_gt_f32_e64 s[44:45], s23, v131
	v_cvt_pk_bf16_f32 v142, v142, v143
	v_cvt_pk_bf16_f32 v143, v144, v145
	s_nop 0
	s_nop 0
	v_cvt_pk_bf16_f32 v144, v148, v149
	v_cvt_pk_bf16_f32 v145, v146, v147
	v_pk_mul_f32 v[146:147], v[108:109], v[176:177] op_sel_hi:[1,0]
	s_nop 0
	s_nop 0
	ds_read_b32 v132, v242 offset:640
	v_mad_i64_i32 v[136:137], s[44:45], v162, s94, v[134:135]
	global_store_dwordx4 v[136:137], v[142:145], off
	v_pk_mul_f32 v[148:149], v[106:107], v[176:177] op_sel_hi:[1,0]
	v_cmp_gt_f32_e32 vcc, s23, v138
	v_pk_mul_f32 v[144:145], v[116:117], v[176:177] op_sel_hi:[1,0]
	v_pk_mul_f32 v[142:143], v[114:115], v[176:177] op_sel_hi:[1,0]
	v_mul_f32_e32 v139, 0x4b800000, v138
	v_cvt_pk_bf16_f32 v142, v142, v143
	v_cvt_pk_bf16_f32 v143, v144, v145
	v_cvt_pk_bf16_f32 v144, v148, v149
	v_cvt_pk_bf16_f32 v145, v146, v147
	global_store_dwordx4 v[136:137], v[142:145], off offset:256
	s_waitcnt lgkmcnt(0)
	v_pk_mul_f32 v[146:147], v[112:113], v[172:173] op_sel_hi:[1,0]
	v_pk_mul_f32 v[148:149], v[110:111], v[172:173] op_sel_hi:[1,0]
	v_pk_mul_f32 v[144:145], v[120:121], v[172:173] op_sel_hi:[1,0]
	v_pk_mul_f32 v[142:143], v[118:119], v[172:173] op_sel_hi:[1,0]
	v_mad_i64_i32 v[136:137], s[44:45], v168, s94, v[134:135]
	v_cvt_pk_bf16_f32 v142, v142, v143
	v_cvt_pk_bf16_f32 v143, v144, v145
	v_cvt_pk_bf16_f32 v144, v148, v149
	v_cvt_pk_bf16_f32 v145, v146, v147
	global_store_dwordx4 v[136:137], v[142:145], off
	v_pk_mul_f32 v[146:147], v[92:93], v[172:173] op_sel_hi:[1,0]
	v_pk_mul_f32 v[148:149], v[90:91], v[172:173] op_sel_hi:[1,0]
	v_pk_mul_f32 v[144:145], v[100:101], v[172:173] op_sel_hi:[1,0]
	v_pk_mul_f32 v[142:143], v[98:99], v[172:173] op_sel_hi:[1,0]
	v_cndmask_b32_e32 v138, v138, v139, vcc
	v_cvt_pk_bf16_f32 v142, v142, v143
	v_cvt_pk_bf16_f32 v143, v144, v145
	v_cvt_pk_bf16_f32 v144, v148, v149
	v_cvt_pk_bf16_f32 v145, v146, v147
	global_store_dwordx4 v[136:137], v[142:145], off offset:256
	s_waitcnt lgkmcnt(0)
	v_pk_mul_f32 v[146:147], v[96:97], v[174:175] op_sel_hi:[1,0]
	v_pk_mul_f32 v[148:149], v[94:95], v[174:175] op_sel_hi:[1,0]
	v_pk_mul_f32 v[144:145], v[104:105], v[174:175] op_sel_hi:[1,0]
	v_pk_mul_f32 v[142:143], v[102:103], v[174:175] op_sel_hi:[1,0]
	v_mad_i64_i32 v[136:137], s[44:45], v166, s94, v[134:135]
	v_cvt_pk_bf16_f32 v142, v142, v143
	v_cvt_pk_bf16_f32 v143, v144, v145
	v_cvt_pk_bf16_f32 v144, v148, v149
	v_cvt_pk_bf16_f32 v145, v146, v147
	global_store_dwordx4 v[136:137], v[142:145], off
	v_pk_mul_f32 v[146:147], v[76:77], v[174:175] op_sel_hi:[1,0]
	v_pk_mul_f32 v[148:149], v[74:75], v[174:175] op_sel_hi:[1,0]
	v_pk_mul_f32 v[144:145], v[84:85], v[174:175] op_sel_hi:[1,0]
	v_pk_mul_f32 v[142:143], v[82:83], v[174:175] op_sel_hi:[1,0]
	v_rsq_f32_e32 v138, v138
	v_cvt_pk_bf16_f32 v142, v142, v143
	v_cvt_pk_bf16_f32 v143, v144, v145
	v_cvt_pk_bf16_f32 v144, v148, v149
	v_cvt_pk_bf16_f32 v145, v146, v147
	global_store_dwordx4 v[136:137], v[142:145], off offset:256
	s_waitcnt lgkmcnt(0)
	v_pk_mul_f32 v[146:147], v[80:81], v[170:171] op_sel_hi:[1,0]
	v_pk_mul_f32 v[148:149], v[78:79], v[170:171] op_sel_hi:[1,0]
	v_pk_mul_f32 v[144:145], v[88:89], v[170:171] op_sel_hi:[1,0]
	v_pk_mul_f32 v[142:143], v[86:87], v[170:171] op_sel_hi:[1,0]
	v_mad_i64_i32 v[136:137], s[44:45], v164, s94, v[134:135]
	v_cvt_pk_bf16_f32 v142, v142, v143
	v_cvt_pk_bf16_f32 v143, v144, v145
	v_cvt_pk_bf16_f32 v144, v148, v149
	v_cvt_pk_bf16_f32 v145, v146, v147
	global_store_dwordx4 v[136:137], v[142:145], off
	v_pk_mul_f32 v[146:147], v[68:69], v[170:171] op_sel_hi:[1,0]
	v_pk_mul_f32 v[148:149], v[66:67], v[170:171] op_sel_hi:[1,0]
	v_pk_mul_f32 v[144:145], v[72:73], v[170:171] op_sel_hi:[1,0]
	v_pk_mul_f32 v[142:143], v[70:71], v[170:171] op_sel_hi:[1,0]
	v_mul_f32_e32 v139, 0x45800000, v138
	v_cvt_pk_bf16_f32 v142, v142, v143
	v_cvt_pk_bf16_f32 v143, v144, v145
	v_cvt_pk_bf16_f32 v144, v148, v149
	v_cvt_pk_bf16_f32 v145, v146, v147
	global_store_dwordx4 v[136:137], v[142:145], off offset:256
	s_waitcnt lgkmcnt(0)
	v_pk_mul_f32 v[146:147], v[60:61], v[140:141] op_sel_hi:[1,0]
	v_pk_mul_f32 v[148:149], v[58:59], v[140:141] op_sel_hi:[1,0]
	v_pk_mul_f32 v[144:145], v[64:65], v[140:141] op_sel_hi:[1,0]
	v_pk_mul_f32 v[142:143], v[62:63], v[140:141] op_sel_hi:[1,0]
	v_mad_i64_i32 v[136:137], s[44:45], v210, s94, v[134:135]
	v_cvt_pk_bf16_f32 v142, v142, v143
	v_cvt_pk_bf16_f32 v143, v144, v145
	v_cvt_pk_bf16_f32 v144, v148, v149
	v_cvt_pk_bf16_f32 v145, v146, v147
	global_store_dwordx4 v[136:137], v[142:145], off
	v_pk_mul_f32 v[146:147], v[44:45], v[140:141] op_sel_hi:[1,0]
	v_pk_mul_f32 v[148:149], v[42:43], v[140:141] op_sel_hi:[1,0]
	v_pk_mul_f32 v[142:143], v[48:49], v[140:141] op_sel_hi:[1,0]
	v_pk_mul_f32 v[144:145], v[46:47], v[140:141] op_sel_hi:[1,0]
	s_nop 0
	ds_read_b32 v138, v242 offset:576
	v_cvt_pk_bf16_f32 v140, v144, v145
	v_cvt_pk_bf16_f32 v141, v142, v143
	v_cvt_pk_bf16_f32 v142, v148, v149
	v_cvt_pk_bf16_f32 v143, v146, v147
	v_cmp_gt_f32_e32 vcc, s23, v130
	v_mul_f32_e32 v131, 0x4b800000, v130
	global_store_dwordx4 v[136:137], v[140:143], off offset:256
	s_waitcnt lgkmcnt(0)
; __device__ __forceinline__ unsigned cvt_pk_bf16(float lo, float hi) { const f32x2_t v = {lo, hi}; return __builtin_bit_cast(unsigned, __builtin_convertvector(v, bf16x2_t)); }
;     __device__ __forceinline__ void plain(const f32x4 (&acc)[2][2][4][2], bf16_t* base, int ld, int colbase, int row0, int cl) const {
;     ...
; #pragma unroll
;         for (int ai = 0; ai < 2; ++ai)
; #pragma unroll
;             for (int m = 0; m < 4; ++m) {
;                 const int row = row0 + ai * HALF + m * 16;
;                 const float rs = rsv[ai][m];
;                 bf16_t* rp = base + (size_t)row * ld + colbase + cl;
; #pragma unroll
;                 for (int bj = 0; bj < 2; ++bj) {
;                     const f32x4 v0 = acc[ai][bj][m][0] * rs, v1 = acc[ai][bj][m][1] * rs;
;                     u32x4 w; w.x = cvt_pk_bf16(v0[0], v0[1]); w.y = cvt_pk_bf16(v0[2], v0[3]); w.z = cvt_pk_bf16(v1[0], v1[1]); w.w = cvt_pk_bf16(v1[2], v1[3]);
;                     *(u32x4*)(rp + bj * HALF) = w;
;                 }
;             }
;     __device__ __forceinline__ void operator()(const f32x4 (&acc)[2][2][4][2], const Unit& u, int wr, int wc, int fr, int fq) const {
;     ...
;         } else if (mode == M_CONV_IN) {
;             if (u.pn < 8) plain(acc, (bf16_t*)(tmp + TC_GB), D, u.pn * BM, row0, cl);
;             else gated<0>(acc, (bf16_t*)(tmp + TC_CU), D, (u.pn - 8) * HALF, row0, cl);
	v_pk_mul_f32 v[136:137], v[56:57], v[138:139] op_sel_hi:[1,0]
	v_pk_mul_f32 v[146:147], v[52:53], v[138:139] op_sel_hi:[1,0]
	v_pk_mul_f32 v[140:141], v[54:55], v[138:139] op_sel_hi:[1,0]
	v_pk_mul_f32 v[142:143], v[50:51], v[138:139] op_sel_hi:[1,0]
	v_cndmask_b32_e32 v130, v130, v131, vcc
	v_mad_i64_i32 v[144:145], s[44:45], v208, s94, v[134:135]
	v_cvt_pk_bf16_f32 v140, v140, v141
	v_cvt_pk_bf16_f32 v141, v136, v137
	v_cvt_pk_bf16_f32 v142, v142, v143
	v_cvt_pk_bf16_f32 v143, v146, v147
	v_rsq_f32_e32 v130, v130
	global_store_dwordx4 v[144:145], v[140:143], off
	v_pk_mul_f32 v[136:137], v[30:31], v[138:139] op_sel_hi:[1,0]
	v_mul_f32_e32 v131, 0x45800000, v130
	v_pk_mul_f32 v[140:141], v[32:33], v[138:139] op_sel_hi:[1,0]
	v_pk_mul_f32 v[142:143], v[28:29], v[138:139] op_sel_hi:[1,0]
	v_pk_mul_f32 v[138:139], v[26:27], v[138:139] op_sel_hi:[1,0]
	v_cvt_pk_bf16_f32 v136, v136, v137
	v_cvt_pk_bf16_f32 v137, v140, v141
	v_cvt_pk_bf16_f32 v138, v138, v139
	v_cvt_pk_bf16_f32 v139, v142, v143
	global_store_dwordx4 v[144:145], v[136:139], off offset:256
	s_waitcnt lgkmcnt(0)
	v_pk_mul_f32 v[142:143], v[36:37], v[132:133] op_sel_hi:[1,0]
	v_pk_mul_f32 v[144:145], v[34:35], v[132:133] op_sel_hi:[1,0]
	v_pk_mul_f32 v[138:139], v[40:41], v[132:133] op_sel_hi:[1,0]
	v_pk_mul_f32 v[136:137], v[38:39], v[132:133] op_sel_hi:[1,0]
	v_mad_i64_i32 v[140:141], s[44:45], v206, s94, v[134:135]
	v_cvt_pk_bf16_f32 v136, v136, v137
	v_cvt_pk_bf16_f32 v137, v138, v139
	v_cvt_pk_bf16_f32 v138, v144, v145
	v_cvt_pk_bf16_f32 v139, v142, v143
	global_store_dwordx4 v[140:141], v[136:139], off
	v_pk_mul_f32 v[142:143], v[12:13], v[132:133] op_sel_hi:[1,0]
	s_nop 0
	ds_read_b32 v130, v242 offset:704
	v_pk_mul_f32 v[138:139], v[16:17], v[132:133] op_sel_hi:[1,0]
	v_pk_mul_f32 v[136:137], v[14:15], v[132:133] op_sel_hi:[1,0]
	v_pk_mul_f32 v[132:133], v[10:11], v[132:133] op_sel_hi:[1,0]
	v_cvt_pk_bf16_f32 v136, v136, v137
	v_cvt_pk_bf16_f32 v137, v138, v139
	v_cvt_pk_bf16_f32 v138, v132, v133
	v_cvt_pk_bf16_f32 v139, v142, v143
	global_store_dwordx4 v[140:141], v[136:139], off offset:256
	s_waitcnt lgkmcnt(0)
	v_pk_mul_f32 v[132:133], v[22:23], v[130:131] op_sel_hi:[1,0]
	v_pk_mul_f32 v[140:141], v[18:19], v[130:131] op_sel_hi:[1,0]
	v_mad_i64_i32 v[136:137], s[44:45], v204, s94, v[134:135]
	v_pk_mul_f32 v[134:135], v[24:25], v[130:131] op_sel_hi:[1,0]
	v_pk_mul_f32 v[138:139], v[20:21], v[130:131] op_sel_hi:[1,0]
	v_cvt_pk_bf16_f32 v132, v132, v133
	v_cvt_pk_bf16_f32 v133, v134, v135
	v_cvt_pk_bf16_f32 v134, v140, v141
	v_cvt_pk_bf16_f32 v135, v138, v139
	global_store_dwordx4 v[136:137], v[132:135], off
	v_pk_mul_f32 v[138:139], v[4:5], v[130:131] op_sel_hi:[1,0]
	v_pk_mul_f32 v[140:141], v[2:3], v[130:131] op_sel_hi:[1,0]
	v_pk_mul_f32 v[132:133], v[8:9], v[130:131] op_sel_hi:[1,0]
	v_pk_mul_f32 v[134:135], v[6:7], v[130:131] op_sel_hi:[1,0]
	v_cvt_pk_bf16_f32 v131, v132, v133
	v_cvt_pk_bf16_f32 v130, v134, v135
	v_cvt_pk_bf16_f32 v132, v140, v141
	v_cvt_pk_bf16_f32 v133, v138, v139
	global_store_dwordx4 v[136:137], v[130:133], off offset:256
.LBB0_618:
	s_andn2_b64 vcc, exec, s[54:55]
	s_cbranch_vccnz .LBB0_547
	v_cmp_lt_i32_e32 vcc, v232, v231
	v_ashrrev_i32_e32 v163, 31, v162
	v_or_b32_e32 v160, 16, v162
	v_cndmask_b32_e32 v130, v229, v232, vcc
	v_cmp_lt_i32_e32 vcc, v230, v231
	v_lshlrev_b32_e32 v247, 2, v130
	v_ashrrev_i32_e32 v161, 31, v160
	v_cndmask_b32_e32 v130, v229, v230, vcc
	v_lshlrev_b32_e32 v246, 2, v130
	s_waitcnt lgkmcnt(0)
	v_lshlrev_b64 v[130:131], 7, v[162:163]
	v_lshl_add_u64 v[130:131], v[190:191], 0, v[130:131]
	s_nop 0
	s_nop 0
	v_lshlrev_b64 v[130:131], 7, v[160:161]
	v_lshl_add_u64 v[130:131], v[190:191], 0, v[130:131]
	s_nop 0
	s_nop 0
	v_or_b32_e32 v168, 32, v162
	v_or_b32_e32 v146, 48, v162
	v_ashrrev_i32_e32 v169, 31, v168
	v_ashrrev_i32_e32 v147, 31, v146
	v_lshlrev_b64 v[130:131], 7, v[168:169]
	v_lshlrev_b64 v[138:139], 7, v[146:147]
	v_lshl_add_u64 v[134:135], v[190:191], 0, v[130:131]
	v_lshl_add_u64 v[142:143], v[190:191], 0, v[138:139]
	s_nop 0
	s_nop 0
	s_nop 0
	s_nop 0
	s_nop 0
	s_nop 0
	s_nop 0
	v_add_u32_e32 v208, 0x80, v162
	v_add_u32_e32 v206, 0x90, v162
	v_add_u32_e32 v204, 0xa0, v162
	v_add_u32_e32 v202, 0xb0, v162
	s_cmp_gt_i32 s82, 7
	s_mov_b64 s[44:45], -1
	v_lshlrev_b64 v[216:217], 12, v[162:163]
	v_lshlrev_b64 v[212:213], 12, v[160:161]
	v_lshlrev_b64 v[210:211], 12, v[168:169]
	v_ashrrev_i32_e32 v209, 31, v208
	v_ashrrev_i32_e32 v207, 31, v206
	v_ashrrev_i32_e32 v205, 31, v204
	v_ashrrev_i32_e32 v203, 31, v202
	v_lshlrev_b64 v[214:215], 12, v[146:147]
	s_nop 0
	v_mov_b32_e32 v171, v152
	v_mov_b32_e32 v170, v164
	v_mov_b32_e32 v152, v165
	v_mov_b32_e32 v164, v166
	v_mov_b32_e32 v165, v154
	v_mov_b32_e32 v154, v167
	v_pk_add_f32 v[152:153], v[170:171], v[152:153]
	v_pk_add_f32 v[154:155], v[164:165], v[154:155]
	s_nop 0
	v_pk_add_f32 v[152:153], v[152:153], v[154:155]
	v_mov_b32_e32 v154, v156
	v_mov_b32_e32 v155, v148
	v_mov_b32_e32 v148, v157
	v_pk_add_f32 v[148:149], v[154:155], v[148:149]
	v_mov_b32_e32 v154, v158
	v_mov_b32_e32 v155, v150
	v_mov_b32_e32 v150, v159
	v_pk_add_f32 v[150:151], v[154:155], v[150:151]
	s_nop 0
	v_pk_add_f32 v[148:149], v[148:149], v[150:151]
	s_nop 0
	v_pk_add_f32 v[218:219], v[152:153], v[148:149]
	s_cbranch_scc0 .LBB0_621
; __device__ __forceinline__ void row_rstd8(const float* ssp, int row0, int fq, float (&rs)[2][4]) {
; #pragma unroll
;     for (int ai = 0; ai < 2; ++ai) {
;         f32x4 a[4], b[4];
; #pragma unroll
;         for (int m = 0; m < 4; ++m) { const float* q = ssp + (size_t)(row0 + ai * HALF + m * 16) * 32 + fq * 8; a[m] = *(const f32x4*)q; b[m] = *(const f32x4*)(q + 4); }
; #pragma unroll
;         for (int m = 0; m < 4; ++m) {
;             float s = ((a[m][0] + a[m][1]) + (a[m][2] + a[m][3])) + ((b[m][0] + b[m][1]) + (b[m][2] + b[m][3]));
;             s += __shfl_xor(s, 16); s += __shfl_xor(s, 32);
;             rs[ai][m] = rsqrtf(s * (1.0f / D) + 1e-6f);
;         }
;     }
; }
;     template <int ACT> __device__ __forceinline__ void gated(const f32x4 (&acc)[2][2][4][2], bf16_t* base, int ld, int colbase, int row0, int cl) const {
;         const int fq = (cl >> 3) & 3;
;         const float* ssin = (const float*)(ws + OFF_SUMSQ) + (size_t)ssi * SS_SLOT;
;         float rsv[2][4];
;         row_rstd8(ssin, row0, fq, rsv);
; #pragma unroll
;         for (int ai = 0; ai < 2; ++ai)
; #pragma unroll
;             for (int m = 0; m < 4; ++m) {
;                 const int row = row0 + ai * HALF + m * 16;
;                 const float rs = rsv[ai][m];
	s_nop 0
	s_nop 0
	s_mov_b32 s30, 0x358637bd
	v_mov_b64_e32 v[226:227], s[30:31]
	v_mov_b32_e32 v150, v137
	v_mov_b32_e32 v151, v133
	s_waitcnt lgkmcnt(0)
	v_pk_add_f32 v[146:147], v[218:219], v[146:147]
	s_nop 0
	s_nop 0
	v_mov_b32_e32 v152, v145
	v_mov_b32_e32 v153, v141
	v_lshlrev_b64 v[162:163], 7, v[202:203]
	v_lshl_add_u64 v[162:163], v[190:191], 0, v[162:163]
	s_waitcnt lgkmcnt(0)
	v_pk_add_f32 v[146:147], v[146:147], v[148:149]
	v_mov_b32_e32 v149, v131
	v_pk_fma_f32 v[146:147], v[146:147], s[22:23], v[226:227] op_sel_hi:[1,0,0]
	s_lshl_b32 s96, s82, 8
	s_nop 0
	s_nop 0
	v_cmp_gt_f32_e32 vcc, s23, v146
	v_readlane_b32 s85, v254, 63
	s_nop 0
	s_nop 0
	s_nop 0
	s_nop 0
	s_nop 0
	ds_read_b32 v224, v242 offset:0
	s_nop 0
	s_nop 0
	s_nop 0
	v_mov_b32_e32 v148, v135
	s_nop 0
	s_nop 0
	ds_read_b32 v220, v242 offset:64
	v_mov_b32_e32 v146, v134
	v_mov_b32_e32 v147, v130
	v_pk_add_f32 v[146:147], v[146:147], v[148:149]
	v_mov_b32_e32 v148, v136
	v_mov_b32_e32 v149, v132
	v_pk_add_f32 v[148:149], v[148:149], v[150:151]
	v_mov_b32_e32 v150, v143
	v_pk_add_f32 v[146:147], v[146:147], v[148:149]
	v_mov_b32_e32 v148, v142
	v_mov_b32_e32 v149, v138
	v_mov_b32_e32 v151, v139
	v_pk_add_f32 v[148:149], v[148:149], v[150:151]
	v_mov_b32_e32 v150, v144
	v_mov_b32_e32 v151, v140
	v_pk_add_f32 v[150:151], v[150:151], v[152:153]
	s_nop 0
	v_pk_add_f32 v[148:149], v[148:149], v[150:151]
	v_mov_b32_e32 v151, v146
	v_mov_b32_e32 v150, v148
	v_mov_b32_e32 v146, v149
	v_pk_add_f32 v[146:147], v[150:151], v[146:147]
	s_nop 0
	s_nop 0
	s_waitcnt lgkmcnt(0)
	v_pk_add_f32 v[146:147], v[146:147], v[148:149]
	s_nop 0
	s_nop 0
	s_waitcnt lgkmcnt(0)
	v_pk_add_f32 v[146:147], v[146:147], v[148:149]
	s_nop 0
	v_pk_fma_f32 v[146:147], v[146:147], s[22:23], v[226:227] op_sel_hi:[1,0,0]
	s_nop 0
	v_mul_f32_e32 v148, 0x4b800000, v147
	v_cmp_gt_f32_e64 s[44:45], s23, v147
	v_cmp_gt_f32_e32 vcc, s23, v146
	s_nop 0
	v_cndmask_b32_e64 v147, v147, v148, s[44:45]
	v_rsq_f32_e32 v147, v147
	s_nop 0
	v_mul_f32_e32 v148, 0x45800000, v147
	s_nop 0
	ds_read_b32 v222, v242 offset:128
	v_mul_f32_e32 v147, 0x4b800000, v146
	v_cndmask_b32_e32 v146, v146, v147, vcc
	v_rsq_f32_e32 v146, v146
	s_nop 0
	v_mul_f32_e32 v147, 0x45800000, v146
	s_nop 0
	ds_read_b32 v178, v242 offset:192
	v_lshlrev_b64 v[146:147], 7, v[208:209]
	v_lshl_add_u64 v[146:147], v[190:191], 0, v[146:147]
	s_nop 0
	s_nop 0
	v_lshlrev_b64 v[146:147], 7, v[206:207]
	v_lshl_add_u64 v[146:147], v[190:191], 0, v[146:147]
	s_nop 0
	s_nop 0
	v_lshlrev_b64 v[146:147], 7, v[204:205]
	v_lshl_add_u64 v[146:147], v[190:191], 0, v[146:147]
	s_nop 0
	s_nop 0
	s_nop 0
	s_nop 0
	s_nop 0
	s_nop 0
	s_nop 0
	s_nop 0
	v_mov_b32_e32 v248, v170
	s_nop 0
	v_mov_b32_e32 v249, v174
	v_mov_b32_e32 v174, v171
	v_pk_add_f32 v[170:171], v[248:249], v[174:175]
	v_mov_b32_e32 v174, v172
	v_mov_b32_e32 v175, v176
	v_mov_b32_e32 v176, v173
	v_pk_add_f32 v[172:173], v[174:175], v[176:177]
	s_nop 0
	v_pk_add_f32 v[170:171], v[170:171], v[172:173]
	s_nop 0
	v_mov_b32_e32 v172, v158
	s_nop 0
	v_mov_b32_e32 v173, v154
	v_mov_b32_e32 v154, v159
	v_mov_b32_e32 v158, v160
	v_mov_b32_e32 v159, v156
	v_mov_b32_e32 v156, v161
	v_pk_add_f32 v[154:155], v[172:173], v[154:155]
	v_pk_add_f32 v[156:157], v[158:159], v[156:157]
	s_nop 0
	v_mov_b32_e32 v158, v150
	v_pk_add_f32 v[154:155], v[154:155], v[156:157]
	v_mov_b32_e32 v157, v170
	v_mov_b32_e32 v156, v154
	v_mov_b32_e32 v170, v155
	v_pk_add_f32 v[154:155], v[156:157], v[170:171]
	s_nop 0
	s_nop 0
	s_nop 0
	v_mov_b32_e32 v159, v146
	v_mov_b32_e32 v146, v151
	v_mov_b32_e32 v150, v152
	v_mov_b32_e32 v151, v148
	v_mov_b32_e32 v148, v153
	v_pk_add_f32 v[146:147], v[158:159], v[146:147]
	v_pk_add_f32 v[148:149], v[150:151], v[148:149]
	s_nop 0
	v_mov_b32_e32 v150, v168
	v_pk_add_f32 v[146:147], v[146:147], v[148:149]
	v_mov_b32_e32 v148, v166
	s_nop 0
	v_mov_b32_e32 v149, v162
	v_mov_b32_e32 v162, v167
	v_mov_b32_e32 v151, v164
	v_mov_b32_e32 v164, v169
	v_pk_add_f32 v[148:149], v[148:149], v[162:163]
	v_pk_add_f32 v[150:151], v[150:151], v[164:165]
	s_waitcnt lgkmcnt(0)
	v_pk_add_f32 v[154:155], v[154:155], v[156:157]
	v_pk_add_f32 v[148:149], v[148:149], v[150:151]
	v_mov_b32_e32 v151, v146
	v_mov_b32_e32 v150, v148
	v_mov_b32_e32 v146, v149
	s_nop 0
	s_nop 0
	v_pk_add_f32 v[146:147], v[150:151], v[146:147]
	s_nop 0
	s_nop 0
	s_waitcnt lgkmcnt(0)
	v_pk_mul_f32 v[160:161], v[116:117], v[224:225] op_sel_hi:[1,0]
	s_waitcnt lgkmcnt(2)
	v_pk_add_f32 v[154:155], v[154:155], v[156:157]
	v_pk_mul_f32 v[162:163], v[106:107], v[224:225] op_sel_hi:[1,0]
	v_pk_fma_f32 v[154:155], v[154:155], s[22:23], v[226:227] op_sel_hi:[1,0,0]
	s_waitcnt lgkmcnt(0)
	v_pk_add_f32 v[146:147], v[146:147], v[148:149]
	s_nop 0
	s_nop 0
	s_nop 0
	s_nop 0
	s_nop 0
	s_nop 0
	v_cmp_gt_f32_e32 vcc, s23, v154
	v_pk_mul_f32 v[164:165], v[108:109], v[224:225] op_sel_hi:[1,0]
	s_waitcnt lgkmcnt(0)
; __device__ __forceinline__ float silu_f(float x) { return x * __builtin_amdgcn_rcpf(1.0f + __expf(-x)); }
; __device__ __forceinline__ void row_rstd8(const float* ssp, int row0, int fq, float (&rs)[2][4]) {
;     ...
;         for (int m = 0; m < 4; ++m) {
;             float s = ((a[m][0] + a[m][1]) + (a[m][2] + a[m][3])) + ((b[m][0] + b[m][1]) + (b[m][2] + b[m][3]));
;             s += __shfl_xor(s, 16); s += __shfl_xor(s, 32);
;             rs[ai][m] = rsqrtf(s * (1.0f / D) + 1e-6f);
;         }
;     template <int ACT> __device__ __forceinline__ void gated(const f32x4 (&acc)[2][2][4][2], bf16_t* base, int ld, int colbase, int row0, int cl) const {
;     ...
; #pragma unroll
;         for (int ai = 0; ai < 2; ++ai)
; #pragma unroll
;             for (int m = 0; m < 4; ++m) {
;                 const int row = row0 + ai * HALF + m * 16;
;                 const float rs = rsv[ai][m];
;                 float o[8];
; #pragma unroll
;                 for (int n = 0; n < 2; ++n)
; #pragma unroll
;                     for (int j = 0; j < 4; ++j) {
;                         const float g = acc[ai][0][m][n][j] * rs, u = acc[ai][1][m][n][j] * rs;
;                         o[n * 4 + j] = (ACT ? silu_f(g) : g) * u;
;                     }
;                 *(u32x4*)(base + (size_t)row * ld + colbase + cl) = pack8(o);
;             }
	v_pk_add_f32 v[146:147], v[146:147], v[148:149]
	s_nop 0
	v_pk_fma_f32 v[146:147], v[146:147], s[22:23], v[226:227] op_sel_hi:[1,0,0]
	s_nop 0
	ds_read_b32 v156, v242 offset:512
	v_mul_f32_e32 v155, 0x4b800000, v154
	s_nop 0
	v_cmp_gt_f32_e64 s[44:45], s23, v147
	v_cndmask_b32_e32 v154, v154, v155, vcc
	v_rsq_f32_e32 v154, v154
	s_nop 0
	s_nop 0
	v_mul_f32_e32 v155, 0x45800000, v154
	s_nop 0
	ds_read_b32 v154, v242 offset:576
	s_nop 0
	v_cmp_gt_f32_e32 vcc, s23, v146
	s_nop 0
	ds_read_b32 v150, v242 offset:640
	v_mul_f32_e32 v147, 0x4b800000, v146
	v_cndmask_b32_e32 v146, v146, v147, vcc
	v_rsq_f32_e32 v146, v146
	s_mov_b64 s[44:45], 0x2c6ff800
	v_pk_mul_f32 v[148:149], v[114:115], v[224:225] op_sel_hi:[1,0]
	v_mul_f32_e32 v147, 0x45800000, v146
	s_nop 0
	ds_read_b32 v152, v242 offset:704
	v_lshl_add_u64 v[146:147], v[194:195], 0, s[96:97]
	v_lshl_add_u64 v[158:159], v[146:147], 0, s[44:45]
	v_pk_mul_f32 v[146:147], v[126:127], v[224:225] op_sel_hi:[1,0]
	s_mov_b64 s[44:45], 0
	v_pk_mul_f32 v[146:147], v[146:147], v[148:149]
	v_pk_mul_f32 v[148:149], v[128:129], v[224:225] op_sel_hi:[1,0]
	v_cvt_pk_bf16_f32 v146, v146, v147
	v_pk_mul_f32 v[148:149], v[148:149], v[160:161]
	v_pk_mul_f32 v[160:161], v[122:123], v[224:225] op_sel_hi:[1,0]
	v_cvt_pk_bf16_f32 v147, v148, v149
	v_pk_mul_f32 v[160:161], v[160:161], v[162:163]
	v_pk_mul_f32 v[162:163], v[124:125], v[224:225] op_sel_hi:[1,0]
	v_cvt_pk_bf16_f32 v148, v160, v161
	v_pk_mul_f32 v[162:163], v[162:163], v[164:165]
	v_lshl_add_u64 v[160:161], v[158:159], 0, v[216:217]
	v_cvt_pk_bf16_f32 v149, v162, v163
	global_store_dwordx4 v[160:161], v[146:149], off
	s_waitcnt lgkmcnt(0)
	v_pk_mul_f32 v[160:161], v[100:101], v[220:221] op_sel_hi:[1,0]
	v_pk_mul_f32 v[162:163], v[90:91], v[220:221] op_sel_hi:[1,0]
	v_pk_mul_f32 v[146:147], v[118:119], v[220:221] op_sel_hi:[1,0]
	v_pk_mul_f32 v[148:149], v[98:99], v[220:221] op_sel_hi:[1,0]
	v_pk_mul_f32 v[164:165], v[92:93], v[220:221] op_sel_hi:[1,0]
	v_pk_mul_f32 v[146:147], v[146:147], v[148:149]
	v_pk_mul_f32 v[148:149], v[120:121], v[220:221] op_sel_hi:[1,0]
	v_cvt_pk_bf16_f32 v146, v146, v147
	v_pk_mul_f32 v[148:149], v[148:149], v[160:161]
	v_pk_mul_f32 v[160:161], v[110:111], v[220:221] op_sel_hi:[1,0]
	v_cvt_pk_bf16_f32 v147, v148, v149
	v_pk_mul_f32 v[160:161], v[160:161], v[162:163]
	v_pk_mul_f32 v[162:163], v[112:113], v[220:221] op_sel_hi:[1,0]
	v_cvt_pk_bf16_f32 v148, v160, v161
	v_pk_mul_f32 v[162:163], v[162:163], v[164:165]
	v_lshl_add_u64 v[160:161], v[158:159], 0, v[212:213]
	v_cvt_pk_bf16_f32 v149, v162, v163
	global_store_dwordx4 v[160:161], v[146:149], off
	s_waitcnt lgkmcnt(0)
	v_pk_mul_f32 v[160:161], v[84:85], v[222:223] op_sel_hi:[1,0]
	v_pk_mul_f32 v[162:163], v[74:75], v[222:223] op_sel_hi:[1,0]
	v_pk_mul_f32 v[146:147], v[102:103], v[222:223] op_sel_hi:[1,0]
	v_pk_mul_f32 v[148:149], v[82:83], v[222:223] op_sel_hi:[1,0]
	v_pk_mul_f32 v[164:165], v[76:77], v[222:223] op_sel_hi:[1,0]
	v_pk_mul_f32 v[146:147], v[146:147], v[148:149]
	v_pk_mul_f32 v[148:149], v[104:105], v[222:223] op_sel_hi:[1,0]
	v_cvt_pk_bf16_f32 v146, v146, v147
	v_pk_mul_f32 v[148:149], v[148:149], v[160:161]
	v_pk_mul_f32 v[160:161], v[94:95], v[222:223] op_sel_hi:[1,0]
	v_cvt_pk_bf16_f32 v147, v148, v149
	v_pk_mul_f32 v[160:161], v[160:161], v[162:163]
	v_pk_mul_f32 v[162:163], v[96:97], v[222:223] op_sel_hi:[1,0]
	v_cvt_pk_bf16_f32 v148, v160, v161
	v_pk_mul_f32 v[162:163], v[162:163], v[164:165]
	v_lshl_add_u64 v[160:161], v[158:159], 0, v[210:211]
	v_cvt_pk_bf16_f32 v149, v162, v163
	global_store_dwordx4 v[160:161], v[146:149], off
	s_waitcnt lgkmcnt(0)
	v_pk_mul_f32 v[160:161], v[72:73], v[178:179] op_sel_hi:[1,0]
	v_pk_mul_f32 v[162:163], v[66:67], v[178:179] op_sel_hi:[1,0]
	v_pk_mul_f32 v[146:147], v[86:87], v[178:179] op_sel_hi:[1,0]
	v_pk_mul_f32 v[148:149], v[70:71], v[178:179] op_sel_hi:[1,0]
	v_pk_mul_f32 v[164:165], v[68:69], v[178:179] op_sel_hi:[1,0]
	v_pk_mul_f32 v[146:147], v[146:147], v[148:149]
	v_pk_mul_f32 v[148:149], v[88:89], v[178:179] op_sel_hi:[1,0]
	v_cvt_pk_bf16_f32 v146, v146, v147
	v_pk_mul_f32 v[148:149], v[148:149], v[160:161]
	v_pk_mul_f32 v[160:161], v[78:79], v[178:179] op_sel_hi:[1,0]
	v_cvt_pk_bf16_f32 v147, v148, v149
	v_pk_mul_f32 v[160:161], v[160:161], v[162:163]
	v_pk_mul_f32 v[162:163], v[80:81], v[178:179] op_sel_hi:[1,0]
	v_cvt_pk_bf16_f32 v148, v160, v161
	v_pk_mul_f32 v[162:163], v[162:163], v[164:165]
	v_lshl_add_u64 v[160:161], v[158:159], 0, v[214:215]
	v_cvt_pk_bf16_f32 v149, v162, v163
	global_store_dwordx4 v[160:161], v[146:149], off
	s_waitcnt lgkmcnt(0)
	v_pk_mul_f32 v[160:161], v[48:49], v[156:157] op_sel_hi:[1,0]
	v_pk_mul_f32 v[162:163], v[42:43], v[156:157] op_sel_hi:[1,0]
	v_pk_mul_f32 v[146:147], v[62:63], v[156:157] op_sel_hi:[1,0]
	v_pk_mul_f32 v[148:149], v[46:47], v[156:157] op_sel_hi:[1,0]
	s_nop 0
	v_pk_mul_f32 v[146:147], v[146:147], v[148:149]
	v_pk_mul_f32 v[148:149], v[64:65], v[156:157] op_sel_hi:[1,0]
	v_cvt_pk_bf16_f32 v146, v146, v147
	v_pk_mul_f32 v[148:149], v[148:149], v[160:161]
	v_pk_mul_f32 v[160:161], v[58:59], v[156:157] op_sel_hi:[1,0]
	v_cvt_pk_bf16_f32 v147, v148, v149
	v_pk_mul_f32 v[160:161], v[160:161], v[162:163]
	v_pk_mul_f32 v[162:163], v[60:61], v[156:157] op_sel_hi:[1,0]
	v_pk_mul_f32 v[156:157], v[44:45], v[156:157] op_sel_hi:[1,0]
	v_cvt_pk_bf16_f32 v148, v160, v161
	v_pk_mul_f32 v[156:157], v[162:163], v[156:157]
	s_waitcnt lgkmcnt(0)
; __device__ __forceinline__ float silu_f(float x) { return x * __builtin_amdgcn_rcpf(1.0f + __expf(-x)); }
; __device__ __forceinline__ void row_rstd8(const float* ssp, int row0, int fq, float (&rs)[2][4]) {
; #pragma unroll
;     for (int ai = 0; ai < 2; ++ai) {
;         f32x4 a[4], b[4];
; #pragma unroll
;         for (int m = 0; m < 4; ++m) { const float* q = ssp + (size_t)(row0 + ai * HALF + m * 16) * 32 + fq * 8; a[m] = *(const f32x4*)q; b[m] = *(const f32x4*)(q + 4); }
; #pragma unroll
;         for (int m = 0; m < 4; ++m) {
;             float s = ((a[m][0] + a[m][1]) + (a[m][2] + a[m][3])) + ((b[m][0] + b[m][1]) + (b[m][2] + b[m][3]));
;             s += __shfl_xor(s, 16); s += __shfl_xor(s, 32);
;             rs[ai][m] = rsqrtf(s * (1.0f / D) + 1e-6f);
;         }
;     }
; }
;     template <int ACT> __device__ __forceinline__ void gated(const f32x4 (&acc)[2][2][4][2], bf16_t* base, int ld, int colbase, int row0, int cl) const {
;     ...
;                 const int row = row0 + ai * HALF + m * 16;
;                 const float rs = rsv[ai][m];
;                 float o[8];
; #pragma unroll
;                 for (int n = 0; n < 2; ++n)
; #pragma unroll
;                     for (int j = 0; j < 4; ++j) {
;                         const float g = acc[ai][0][m][n][j] * rs, u = acc[ai][1][m][n][j] * rs;
;                         o[n * 4 + j] = (ACT ? silu_f(g) : g) * u;
;                     }
;                 *(u32x4*)(base + (size_t)row * ld + colbase + cl) = pack8(o);
	v_pk_mul_f32 v[160:161], v[26:27], v[154:155] op_sel_hi:[1,0]
	v_cvt_pk_bf16_f32 v149, v156, v157
	v_lshlrev_b64 v[156:157], 12, v[208:209]
	v_lshl_add_u64 v[156:157], v[158:159], 0, v[156:157]
	global_store_dwordx4 v[156:157], v[146:149], off
	v_pk_mul_f32 v[156:157], v[32:33], v[154:155] op_sel_hi:[1,0]
	s_nop 0
	v_pk_mul_f32 v[146:147], v[54:55], v[154:155] op_sel_hi:[1,0]
	v_pk_mul_f32 v[148:149], v[30:31], v[154:155] op_sel_hi:[1,0]
	s_nop 0
	v_pk_mul_f32 v[146:147], v[146:147], v[148:149]
	v_pk_mul_f32 v[148:149], v[56:57], v[154:155] op_sel_hi:[1,0]
	v_cvt_pk_bf16_f32 v146, v146, v147
	v_pk_mul_f32 v[148:149], v[148:149], v[156:157]
	v_pk_mul_f32 v[156:157], v[50:51], v[154:155] op_sel_hi:[1,0]
	v_cvt_pk_bf16_f32 v147, v148, v149
	v_pk_mul_f32 v[156:157], v[156:157], v[160:161]
	v_pk_mul_f32 v[160:161], v[52:53], v[154:155] op_sel_hi:[1,0]
	v_pk_mul_f32 v[154:155], v[28:29], v[154:155] op_sel_hi:[1,0]
	v_cvt_pk_bf16_f32 v148, v156, v157
	v_pk_mul_f32 v[154:155], v[160:161], v[154:155]
	s_waitcnt lgkmcnt(0)
	v_pk_mul_f32 v[156:157], v[10:11], v[150:151] op_sel_hi:[1,0]
	v_cvt_pk_bf16_f32 v149, v154, v155
	v_lshlrev_b64 v[154:155], 12, v[206:207]
	v_lshl_add_u64 v[154:155], v[158:159], 0, v[154:155]
	global_store_dwordx4 v[154:155], v[146:149], off
	v_pk_mul_f32 v[154:155], v[16:17], v[150:151] op_sel_hi:[1,0]
	s_nop 0
	v_pk_mul_f32 v[146:147], v[38:39], v[150:151] op_sel_hi:[1,0]
	v_pk_mul_f32 v[148:149], v[14:15], v[150:151] op_sel_hi:[1,0]
	s_nop 0
	v_pk_mul_f32 v[146:147], v[146:147], v[148:149]
	v_pk_mul_f32 v[148:149], v[40:41], v[150:151] op_sel_hi:[1,0]
	v_cvt_pk_bf16_f32 v146, v146, v147
	v_pk_mul_f32 v[148:149], v[148:149], v[154:155]
	v_pk_mul_f32 v[154:155], v[34:35], v[150:151] op_sel_hi:[1,0]
	v_cvt_pk_bf16_f32 v147, v148, v149
	v_pk_mul_f32 v[154:155], v[154:155], v[156:157]
	v_pk_mul_f32 v[156:157], v[36:37], v[150:151] op_sel_hi:[1,0]
	v_pk_mul_f32 v[150:151], v[12:13], v[150:151] op_sel_hi:[1,0]
	v_cvt_pk_bf16_f32 v148, v154, v155
	v_pk_mul_f32 v[150:151], v[156:157], v[150:151]
	s_waitcnt lgkmcnt(0)
	v_pk_mul_f32 v[154:155], v[2:3], v[152:153] op_sel_hi:[1,0]
	v_cvt_pk_bf16_f32 v149, v150, v151
	v_lshlrev_b64 v[150:151], 12, v[204:205]
	v_lshl_add_u64 v[150:151], v[158:159], 0, v[150:151]
	global_store_dwordx4 v[150:151], v[146:149], off
	v_pk_mul_f32 v[150:151], v[8:9], v[152:153] op_sel_hi:[1,0]
	s_nop 0
	v_pk_mul_f32 v[146:147], v[22:23], v[152:153] op_sel_hi:[1,0]
	v_pk_mul_f32 v[148:149], v[6:7], v[152:153] op_sel_hi:[1,0]
	s_nop 0
	v_pk_mul_f32 v[146:147], v[146:147], v[148:149]
	v_pk_mul_f32 v[148:149], v[24:25], v[152:153] op_sel_hi:[1,0]
	v_cvt_pk_bf16_f32 v146, v146, v147
	v_pk_mul_f32 v[148:149], v[148:149], v[150:151]
	v_pk_mul_f32 v[150:151], v[18:19], v[152:153] op_sel_hi:[1,0]
	v_cvt_pk_bf16_f32 v147, v148, v149
	v_pk_mul_f32 v[150:151], v[150:151], v[154:155]
	v_pk_mul_f32 v[154:155], v[20:21], v[152:153] op_sel_hi:[1,0]
	v_pk_mul_f32 v[152:153], v[4:5], v[152:153] op_sel_hi:[1,0]
	v_cvt_pk_bf16_f32 v148, v150, v151
	v_pk_mul_f32 v[152:153], v[154:155], v[152:153]
	v_lshlrev_b64 v[150:151], 12, v[202:203]
	v_cvt_pk_bf16_f32 v149, v152, v153
	v_lshl_add_u64 v[150:151], v[158:159], 0, v[150:151]
	global_store_dwordx4 v[150:151], v[146:149], off
.LBB0_621:
	s_andn2_b64 vcc, exec, s[44:45]
	s_cbranch_vccnz .LBB0_547
	s_nop 0
	s_nop 0
	s_mov_b32 s30, 0x358637bd
	v_mov_b64_e32 v[170:171], s[30:31]
	s_lshl_b32 s54, s82, 8
	s_ashr_i32 s55, s54, 31
	s_waitcnt lgkmcnt(0)
	v_pk_add_f32 v[146:147], v[218:219], v[146:147]
	s_nop 0
	s_nop 0
	s_waitcnt lgkmcnt(0)
	v_pk_add_f32 v[146:147], v[146:147], v[148:149]
	s_nop 0
	v_pk_fma_f32 v[146:147], v[146:147], s[22:23], v[170:171] op_sel_hi:[1,0,0]
	s_nop 0
	v_mul_f32_e32 v148, 0x4b800000, v147
	v_cmp_gt_f32_e64 s[44:45], s23, v147
	v_cmp_gt_f32_e32 vcc, s23, v146
	s_nop 0
	v_cndmask_b32_e64 v147, v147, v148, s[44:45]
	v_rsq_f32_e32 v147, v147
	s_nop 0
	v_mul_f32_e32 v148, 0x45800000, v147
	s_nop 0
	ds_read_b32 v168, v242 offset:0
	s_nop 0
	s_nop 0
	s_nop 0
	s_waitcnt lgkmcnt(0)
	v_pk_mul_f32 v[128:129], v[128:129], v[168:169] op_sel_hi:[1,0]
	v_pk_mul_f32 v[126:127], v[126:127], v[168:169] op_sel_hi:[1,0]
	v_pk_mul_f32 v[116:117], v[116:117], v[168:169] op_sel_hi:[1,0]
	s_nop 0
	s_nop 0
	ds_read_b32 v164, v242 offset:64
	v_mov_b32_e32 v146, v134
	v_mov_b32_e32 v147, v130
	v_mov_b32_e32 v130, v135
	v_mov_b32_e32 v134, v136
	v_mov_b32_e32 v135, v132
	v_mov_b32_e32 v132, v137
	v_pk_add_f32 v[130:131], v[146:147], v[130:131]
	v_pk_add_f32 v[132:133], v[134:135], v[132:133]
	v_mov_b32_e32 v134, v144
	v_pk_add_f32 v[130:131], v[130:131], v[132:133]
	v_mov_b32_e32 v132, v142
	v_mov_b32_e32 v133, v138
	v_mov_b32_e32 v138, v143
	v_mov_b32_e32 v135, v140
	v_mov_b32_e32 v140, v145
	v_pk_add_f32 v[132:133], v[132:133], v[138:139]
	v_pk_add_f32 v[134:135], v[134:135], v[140:141]
	v_lshlrev_b64 v[138:139], 7, v[202:203]
	v_pk_add_f32 v[132:133], v[132:133], v[134:135]
	v_mov_b32_e32 v135, v130
	v_mov_b32_e32 v134, v132
	v_mov_b32_e32 v130, v133
	v_pk_add_f32 v[130:131], v[134:135], v[130:131]
	s_nop 0
	s_nop 0
	v_lshl_add_u64 v[138:139], v[190:191], 0, v[138:139]
	v_pk_mul_f32 v[114:115], v[114:115], v[168:169] op_sel_hi:[1,0]
	s_waitcnt lgkmcnt(0)
	v_pk_mul_f32 v[112:113], v[112:113], v[164:165] op_sel_hi:[1,0]
	v_pk_mul_f32 v[110:111], v[110:111], v[164:165] op_sel_hi:[1,0]
	s_waitcnt lgkmcnt(0)
	v_pk_add_f32 v[130:131], v[130:131], v[132:133]
	s_nop 0
	s_nop 0
	v_pk_mul_f32 v[100:101], v[100:101], v[164:165] op_sel_hi:[1,0]
	v_pk_mul_f32 v[98:99], v[98:99], v[164:165] op_sel_hi:[1,0]
	s_waitcnt lgkmcnt(0)
; __device__ __forceinline__ unsigned cvt_pk_bf16(float lo, float hi) { const f32x2_t v = {lo, hi}; return __builtin_bit_cast(unsigned, __builtin_convertvector(v, bf16x2_t)); }
; __device__ __forceinline__ void row_rstd8(const float* ssp, int row0, int fq, float (&rs)[2][4]) {
; #pragma unroll
;     for (int ai = 0; ai < 2; ++ai) {
;         f32x4 a[4], b[4];
; #pragma unroll
;         for (int m = 0; m < 4; ++m) { const float* q = ssp + (size_t)(row0 + ai * HALF + m * 16) * 32 + fq * 8; a[m] = *(const f32x4*)q; b[m] = *(const f32x4*)(q + 4); }
; #pragma unroll
;         for (int m = 0; m < 4; ++m) {
;             float s = ((a[m][0] + a[m][1]) + (a[m][2] + a[m][3])) + ((b[m][0] + b[m][1]) + (b[m][2] + b[m][3]));
;             s += __shfl_xor(s, 16); s += __shfl_xor(s, 32);
;             rs[ai][m] = rsqrtf(s * (1.0f / D) + 1e-6f);
;         }
;     }
; }
;     __device__ __forceinline__ void plain(const f32x4 (&acc)[2][2][4][2], bf16_t* base, int ld, int colbase, int row0, int cl) const {
;         const int fq = (cl >> 3) & 3;
;         const float* ssin = (const float*)(ws + OFF_SUMSQ) + (size_t)ssi * SS_SLOT;
;         float rsv[2][4];
;         row_rstd8(ssin, row0, fq, rsv);
; #pragma unroll
;         for (int ai = 0; ai < 2; ++ai)
; #pragma unroll
;             for (int m = 0; m < 4; ++m) {
;                 const int row = row0 + ai * HALF + m * 16;
;                 const float rs = rsv[ai][m];
;                 bf16_t* rp = base + (size_t)row * ld + colbase + cl;
; #pragma unroll
;                 for (int bj = 0; bj < 2; ++bj) {
;                     const f32x4 v0 = acc[ai][bj][m][0] * rs, v1 = acc[ai][bj][m][1] * rs;
;                     u32x4 w; w.x = cvt_pk_bf16(v0[0], v0[1]); w.y = cvt_pk_bf16(v0[2], v0[3]); w.z = cvt_pk_bf16(v1[0], v1[1]); w.w = cvt_pk_bf16(v1[2], v1[3]);
;                     *(u32x4*)(rp + bj * HALF) = w;
;                 }
;             }
	v_pk_add_f32 v[130:131], v[130:131], v[132:133]
	s_nop 0
	v_pk_fma_f32 v[130:131], v[130:131], s[22:23], v[170:171] op_sel_hi:[1,0,0]
	s_nop 0
	v_mul_f32_e32 v132, 0x4b800000, v131
	v_cmp_gt_f32_e64 s[44:45], s23, v131
	v_cmp_gt_f32_e32 vcc, s23, v130
	s_nop 0
	v_cndmask_b32_e64 v131, v131, v132, s[44:45]
	v_rsq_f32_e32 v131, v131
	s_nop 0
	v_mul_f32_e32 v132, 0x45800000, v131
	s_nop 0
	ds_read_b32 v166, v242 offset:128
	v_mul_f32_e32 v131, 0x4b800000, v130
	v_cndmask_b32_e32 v130, v130, v131, vcc
	v_rsq_f32_e32 v130, v130
	s_waitcnt lgkmcnt(0)
	v_pk_mul_f32 v[96:97], v[96:97], v[166:167] op_sel_hi:[1,0]
	v_pk_mul_f32 v[94:95], v[94:95], v[166:167] op_sel_hi:[1,0]
	v_pk_mul_f32 v[84:85], v[84:85], v[166:167] op_sel_hi:[1,0]
	v_mul_f32_e32 v131, 0x45800000, v130
	s_nop 0
	ds_read_b32 v162, v242 offset:192
	v_lshlrev_b64 v[130:131], 7, v[208:209]
	v_lshl_add_u64 v[130:131], v[190:191], 0, v[130:131]
	s_nop 0
	s_nop 0
	v_lshlrev_b64 v[130:131], 7, v[206:207]
	v_lshl_add_u64 v[130:131], v[190:191], 0, v[130:131]
	s_nop 0
	s_nop 0
	v_lshlrev_b64 v[130:131], 7, v[204:205]
	v_lshl_add_u64 v[130:131], v[190:191], 0, v[130:131]
	s_nop 0
	s_nop 0
	s_nop 0
	s_nop 0
	s_nop 0
	s_nop 0
	s_nop 0
	v_pk_mul_f32 v[82:83], v[82:83], v[166:167] op_sel_hi:[1,0]
	s_waitcnt lgkmcnt(0)
	v_pk_mul_f32 v[80:81], v[80:81], v[162:163] op_sel_hi:[1,0]
	v_pk_mul_f32 v[78:79], v[78:79], v[162:163] op_sel_hi:[1,0]
	v_pk_mul_f32 v[72:73], v[72:73], v[162:163] op_sel_hi:[1,0]
	v_pk_mul_f32 v[70:71], v[70:71], v[162:163] op_sel_hi:[1,0]
	s_nop 0
	v_mov_b32_e32 v172, v154
	s_nop 0
	v_mov_b32_e32 v173, v158
	v_mov_b32_e32 v158, v155
	v_pk_add_f32 v[154:155], v[172:173], v[158:159]
	v_mov_b32_e32 v158, v156
	v_mov_b32_e32 v159, v160
	v_mov_b32_e32 v160, v157
	v_pk_add_f32 v[156:157], v[158:159], v[160:161]
	s_nop 0
	v_pk_add_f32 v[154:155], v[154:155], v[156:157]
	s_nop 0
	v_mov_b32_e32 v156, v150
	s_nop 0
	v_mov_b32_e32 v157, v146
	v_mov_b32_e32 v146, v151
	v_mov_b32_e32 v150, v152
	v_mov_b32_e32 v151, v148
	v_mov_b32_e32 v148, v153
	v_pk_add_f32 v[146:147], v[156:157], v[146:147]
	v_pk_add_f32 v[148:149], v[150:151], v[148:149]
	s_nop 0
	v_mov_b32_e32 v150, v134
	v_pk_add_f32 v[146:147], v[146:147], v[148:149]
	v_mov_b32_e32 v149, v154
	v_mov_b32_e32 v148, v146
	v_mov_b32_e32 v154, v147
	v_pk_add_f32 v[146:147], v[148:149], v[154:155]
	s_nop 0
	s_nop 0
	s_nop 0
	v_mov_b32_e32 v151, v130
	v_mov_b32_e32 v130, v135
	v_mov_b32_e32 v134, v136
	v_mov_b32_e32 v135, v132
	v_mov_b32_e32 v132, v137
	v_pk_add_f32 v[130:131], v[150:151], v[130:131]
	v_pk_add_f32 v[132:133], v[134:135], v[132:133]
	s_nop 0
	v_mov_b32_e32 v134, v144
	v_pk_add_f32 v[130:131], v[130:131], v[132:133]
	v_mov_b32_e32 v132, v142
	s_nop 0
	v_mov_b32_e32 v133, v138
	v_mov_b32_e32 v138, v143
	v_mov_b32_e32 v135, v140
	v_mov_b32_e32 v140, v145
	v_pk_add_f32 v[132:133], v[132:133], v[138:139]
	v_pk_add_f32 v[134:135], v[134:135], v[140:141]
	s_waitcnt lgkmcnt(0)
	v_pk_add_f32 v[146:147], v[146:147], v[148:149]
	v_pk_add_f32 v[132:133], v[132:133], v[134:135]
	s_nop 0
	s_nop 0
	v_mov_b32_e32 v134, v132
	v_mov_b32_e32 v135, v130
	v_mov_b32_e32 v130, v133
	v_pk_add_f32 v[130:131], v[134:135], v[130:131]
	v_lshl_add_u64 v[134:135], s[54:55], 1, v[188:189]
	v_pk_mul_f32 v[138:139], v[124:125], v[168:169] op_sel_hi:[1,0]
	v_pk_mul_f32 v[124:125], v[122:123], v[168:169] op_sel_hi:[1,0]
	v_lshl_add_u64 v[136:137], v[134:135], 0, v[216:217]
	v_cvt_pk_bf16_f32 v122, v126, v127
	v_cvt_pk_bf16_f32 v123, v128, v129
	v_cvt_pk_bf16_f32 v124, v124, v125
	v_cvt_pk_bf16_f32 v125, v138, v139
	global_store_dwordx4 v[136:137], v[122:125], off
	s_nop 0
	s_nop 0
	v_pk_mul_f32 v[122:123], v[108:109], v[168:169] op_sel_hi:[1,0]
	v_pk_mul_f32 v[108:109], v[106:107], v[168:169] op_sel_hi:[1,0]
	v_cvt_pk_bf16_f32 v106, v114, v115
	v_cvt_pk_bf16_f32 v107, v116, v117
	v_cvt_pk_bf16_f32 v108, v108, v109
	v_cvt_pk_bf16_f32 v109, v122, v123
	s_waitcnt lgkmcnt(2)
	v_pk_add_f32 v[146:147], v[146:147], v[148:149]
	global_store_dwordx4 v[136:137], v[106:109], off offset:256
	v_pk_fma_f32 v[146:147], v[146:147], s[22:23], v[170:171] op_sel_hi:[1,0,0]
	v_lshl_add_u64 v[114:115], v[134:135], 0, v[212:213]
	v_pk_mul_f32 v[108:109], v[120:121], v[164:165] op_sel_hi:[1,0]
	v_pk_mul_f32 v[106:107], v[118:119], v[164:165] op_sel_hi:[1,0]
	s_nop 0
	v_cvt_pk_bf16_f32 v106, v106, v107
	v_cvt_pk_bf16_f32 v107, v108, v109
	v_cvt_pk_bf16_f32 v108, v110, v111
	v_cvt_pk_bf16_f32 v109, v112, v113
	s_nop 0
	global_store_dwordx4 v[114:115], v[106:109], off
	s_waitcnt lgkmcnt(0)
	v_pk_add_f32 v[130:131], v[130:131], v[132:133]
	s_nop 0
	v_pk_mul_f32 v[106:107], v[92:93], v[164:165] op_sel_hi:[1,0]
	v_pk_mul_f32 v[92:93], v[90:91], v[164:165] op_sel_hi:[1,0]
	v_cvt_pk_bf16_f32 v90, v98, v99
	v_cvt_pk_bf16_f32 v91, v100, v101
	v_cvt_pk_bf16_f32 v92, v92, v93
	v_cvt_pk_bf16_f32 v93, v106, v107
	s_nop 0
	global_store_dwordx4 v[114:115], v[90:93], off offset:256
	s_nop 0
	s_nop 0
	v_pk_mul_f32 v[92:93], v[104:105], v[166:167] op_sel_hi:[1,0]
	v_pk_mul_f32 v[90:91], v[102:103], v[166:167] op_sel_hi:[1,0]
	v_lshl_add_u64 v[98:99], v[134:135], 0, v[210:211]
	v_cvt_pk_bf16_f32 v90, v90, v91
	v_cvt_pk_bf16_f32 v91, v92, v93
	v_cvt_pk_bf16_f32 v92, v94, v95
	v_cvt_pk_bf16_f32 v93, v96, v97
	global_store_dwordx4 v[98:99], v[90:93], off
	s_nop 0
	v_cmp_gt_f32_e32 vcc, s23, v146
	v_pk_mul_f32 v[90:91], v[76:77], v[166:167] op_sel_hi:[1,0]
	v_pk_mul_f32 v[76:77], v[74:75], v[166:167] op_sel_hi:[1,0]
	v_cvt_pk_bf16_f32 v74, v82, v83
	v_cvt_pk_bf16_f32 v75, v84, v85
	v_cvt_pk_bf16_f32 v76, v76, v77
	v_cvt_pk_bf16_f32 v77, v90, v91
	global_store_dwordx4 v[98:99], v[74:77], off offset:256
	s_nop 0
	ds_read_b32 v148, v242 offset:512
	v_mul_f32_e32 v147, 0x4b800000, v146
	v_pk_mul_f32 v[76:77], v[88:89], v[162:163] op_sel_hi:[1,0]
	v_pk_mul_f32 v[74:75], v[86:87], v[162:163] op_sel_hi:[1,0]
	v_lshl_add_u64 v[82:83], v[134:135], 0, v[214:215]
	v_cvt_pk_bf16_f32 v74, v74, v75
	v_cvt_pk_bf16_f32 v75, v76, v77
	v_cvt_pk_bf16_f32 v76, v78, v79
	v_cvt_pk_bf16_f32 v77, v80, v81
	v_cndmask_b32_e32 v146, v146, v147, vcc
	s_waitcnt lgkmcnt(0)
; __device__ __forceinline__ unsigned cvt_pk_bf16(float lo, float hi) { const f32x2_t v = {lo, hi}; return __builtin_bit_cast(unsigned, __builtin_convertvector(v, bf16x2_t)); }
;     __device__ __forceinline__ void plain(const f32x4 (&acc)[2][2][4][2], bf16_t* base, int ld, int colbase, int row0, int cl) const {
;         const int fq = (cl >> 3) & 3;
;         const float* ssin = (const float*)(ws + OFF_SUMSQ) + (size_t)ssi * SS_SLOT;
;         float rsv[2][4];
;         row_rstd8(ssin, row0, fq, rsv);
; #pragma unroll
;         for (int ai = 0; ai < 2; ++ai)
; #pragma unroll
;             for (int m = 0; m < 4; ++m) {
;                 const int row = row0 + ai * HALF + m * 16;
;                 const float rs = rsv[ai][m];
;                 bf16_t* rp = base + (size_t)row * ld + colbase + cl;
; #pragma unroll
;                 for (int bj = 0; bj < 2; ++bj) {
;                     const f32x4 v0 = acc[ai][bj][m][0] * rs, v1 = acc[ai][bj][m][1] * rs;
;                     u32x4 w; w.x = cvt_pk_bf16(v0[0], v0[1]); w.y = cvt_pk_bf16(v0[2], v0[3]); w.z = cvt_pk_bf16(v1[0], v1[1]); w.w = cvt_pk_bf16(v1[2], v1[3]);
;                     *(u32x4*)(rp + bj * HALF) = w;
;                 }
;             }
	v_pk_add_f32 v[130:131], v[130:131], v[132:133]
	global_store_dwordx4 v[82:83], v[74:77], off
	v_rsq_f32_e32 v146, v146
	v_pk_fma_f32 v[130:131], v[130:131], s[22:23], v[170:171] op_sel_hi:[1,0,0]
	v_pk_mul_f32 v[74:75], v[68:69], v[162:163] op_sel_hi:[1,0]
	v_pk_mul_f32 v[68:69], v[66:67], v[162:163] op_sel_hi:[1,0]
	v_cvt_pk_bf16_f32 v66, v70, v71
	v_cvt_pk_bf16_f32 v67, v72, v73
	v_cvt_pk_bf16_f32 v68, v68, v69
	v_cvt_pk_bf16_f32 v69, v74, v75
	s_nop 0
	v_cmp_gt_f32_e64 s[44:45], s23, v131
	global_store_dwordx4 v[82:83], v[66:69], off offset:256
	s_waitcnt lgkmcnt(0)
	v_pk_mul_f32 v[64:65], v[64:65], v[148:149] op_sel_hi:[1,0]
	v_pk_mul_f32 v[62:63], v[62:63], v[148:149] op_sel_hi:[1,0]
	v_lshlrev_b64 v[66:67], 12, v[208:209]
	v_pk_mul_f32 v[68:69], v[60:61], v[148:149] op_sel_hi:[1,0]
	v_pk_mul_f32 v[60:61], v[58:59], v[148:149] op_sel_hi:[1,0]
	s_nop 0
	v_lshl_add_u64 v[66:67], v[134:135], 0, v[66:67]
	v_cvt_pk_bf16_f32 v58, v62, v63
	v_cvt_pk_bf16_f32 v59, v64, v65
	v_cvt_pk_bf16_f32 v60, v60, v61
	v_cvt_pk_bf16_f32 v61, v68, v69
	s_nop 0
	global_store_dwordx4 v[66:67], v[58:61], off
	v_pk_mul_f32 v[48:49], v[48:49], v[148:149] op_sel_hi:[1,0]
	v_pk_mul_f32 v[46:47], v[46:47], v[148:149] op_sel_hi:[1,0]
	v_pk_mul_f32 v[58:59], v[44:45], v[148:149] op_sel_hi:[1,0]
	v_pk_mul_f32 v[44:45], v[42:43], v[148:149] op_sel_hi:[1,0]
	v_mul_f32_e32 v147, 0x45800000, v146
	v_cvt_pk_bf16_f32 v42, v46, v47
	v_cvt_pk_bf16_f32 v43, v48, v49
	v_cvt_pk_bf16_f32 v44, v44, v45
	v_cvt_pk_bf16_f32 v45, v58, v59
	s_nop 0
	ds_read_b32 v146, v242 offset:576
	global_store_dwordx4 v[66:67], v[42:45], off offset:256
	s_waitcnt lgkmcnt(0)
	v_pk_mul_f32 v[48:49], v[52:53], v[146:147] op_sel_hi:[1,0]
	v_pk_mul_f32 v[50:51], v[50:51], v[146:147] op_sel_hi:[1,0]
	v_lshlrev_b64 v[42:43], 12, v[206:207]
	v_lshl_add_u64 v[46:47], v[134:135], 0, v[42:43]
	v_pk_mul_f32 v[44:45], v[56:57], v[146:147] op_sel_hi:[1,0]
	v_pk_mul_f32 v[42:43], v[54:55], v[146:147] op_sel_hi:[1,0]
	s_nop 0
	v_cvt_pk_bf16_f32 v42, v42, v43
	v_cvt_pk_bf16_f32 v43, v44, v45
	v_cvt_pk_bf16_f32 v44, v50, v51
	v_cvt_pk_bf16_f32 v45, v48, v49
	v_cmp_gt_f32_e32 vcc, s23, v130
	s_nop 0
	ds_read_b32 v132, v242 offset:640
	v_mul_f32_e32 v131, 0x4b800000, v130
	global_store_dwordx4 v[46:47], v[42:45], off
	v_pk_mul_f32 v[32:33], v[32:33], v[146:147] op_sel_hi:[1,0]
	v_pk_mul_f32 v[30:31], v[30:31], v[146:147] op_sel_hi:[1,0]
	v_pk_mul_f32 v[42:43], v[28:29], v[146:147] op_sel_hi:[1,0]
	v_pk_mul_f32 v[28:29], v[26:27], v[146:147] op_sel_hi:[1,0]
	v_cndmask_b32_e32 v130, v130, v131, vcc
	v_cvt_pk_bf16_f32 v26, v30, v31
	v_cvt_pk_bf16_f32 v27, v32, v33
	v_cvt_pk_bf16_f32 v28, v28, v29
	v_cvt_pk_bf16_f32 v29, v42, v43
	v_rsq_f32_e32 v130, v130
	global_store_dwordx4 v[46:47], v[26:29], off offset:256
	s_waitcnt lgkmcnt(0)
	v_pk_mul_f32 v[32:33], v[36:37], v[132:133] op_sel_hi:[1,0]
	v_pk_mul_f32 v[34:35], v[34:35], v[132:133] op_sel_hi:[1,0]
	v_lshlrev_b64 v[26:27], 12, v[204:205]
	v_lshl_add_u64 v[30:31], v[134:135], 0, v[26:27]
	v_pk_mul_f32 v[28:29], v[40:41], v[132:133] op_sel_hi:[1,0]
	v_pk_mul_f32 v[26:27], v[38:39], v[132:133] op_sel_hi:[1,0]
	v_pk_mul_f32 v[16:17], v[16:17], v[132:133] op_sel_hi:[1,0]
	v_cvt_pk_bf16_f32 v26, v26, v27
	v_cvt_pk_bf16_f32 v27, v28, v29
	v_cvt_pk_bf16_f32 v28, v34, v35
	v_cvt_pk_bf16_f32 v29, v32, v33
	global_store_dwordx4 v[30:31], v[26:29], off
	v_pk_mul_f32 v[14:15], v[14:15], v[132:133] op_sel_hi:[1,0]
	v_mul_f32_e32 v131, 0x45800000, v130
	v_pk_mul_f32 v[26:27], v[12:13], v[132:133] op_sel_hi:[1,0]
	v_pk_mul_f32 v[12:13], v[10:11], v[132:133] op_sel_hi:[1,0]
	v_cvt_pk_bf16_f32 v10, v14, v15
	v_cvt_pk_bf16_f32 v11, v16, v17
	v_cvt_pk_bf16_f32 v12, v12, v13
	v_cvt_pk_bf16_f32 v13, v26, v27
	s_nop 0
	ds_read_b32 v130, v242 offset:704
	global_store_dwordx4 v[30:31], v[10:13], off offset:256
	s_waitcnt lgkmcnt(0)
	v_pk_mul_f32 v[16:17], v[20:21], v[130:131] op_sel_hi:[1,0]
	v_pk_mul_f32 v[18:19], v[18:19], v[130:131] op_sel_hi:[1,0]
	v_lshlrev_b64 v[10:11], 12, v[202:203]
	v_lshl_add_u64 v[14:15], v[134:135], 0, v[10:11]
	v_pk_mul_f32 v[12:13], v[24:25], v[130:131] op_sel_hi:[1,0]
	v_pk_mul_f32 v[10:11], v[22:23], v[130:131] op_sel_hi:[1,0]
	v_pk_mul_f32 v[8:9], v[8:9], v[130:131] op_sel_hi:[1,0]
	v_cvt_pk_bf16_f32 v10, v10, v11
	v_cvt_pk_bf16_f32 v11, v12, v13
	v_cvt_pk_bf16_f32 v12, v18, v19
	v_cvt_pk_bf16_f32 v13, v16, v17
	global_store_dwordx4 v[14:15], v[10:13], off
	v_pk_mul_f32 v[6:7], v[6:7], v[130:131] op_sel_hi:[1,0]
	s_nop 0
	v_pk_mul_f32 v[10:11], v[4:5], v[130:131] op_sel_hi:[1,0]
	v_pk_mul_f32 v[4:5], v[2:3], v[130:131] op_sel_hi:[1,0]
	v_cvt_pk_bf16_f32 v2, v6, v7
	v_cvt_pk_bf16_f32 v3, v8, v9
	v_cvt_pk_bf16_f32 v4, v4, v5
	v_cvt_pk_bf16_f32 v5, v10, v11
	global_store_dwordx4 v[14:15], v[2:5], off offset:256
	s_branch .LBB0_547
